# hand-written row passes: 4 LayerNorm phases and init_x with all row loads in flight (no per-chunk load-wait-store serialization)
# speedup vs baseline: 1.0337x; 1.0337x over previous
; DI int otid() { int t = threadIdx.x; asm volatile("" : "+v"(t)); return t; }
; DI void phase_init_x(const Params& p) {
;     const int tid_ = otid(); const int lane = tid_ & 63, gw = blockIdx.x * 8 + (tid_ >> 6), nw = gridDim.x * 8;
;     float* X = (float*)(p.ws + WS_X); bf16_t* H = (bf16_t*)(p.ws + WS_H); const float* mod = (const float*)(p.ws + WS_MOD);
;     for (int row = gw; row < MR; row += nw) {
;         const int b = row / RB, r = row % RB; const int s = r < CL ? 4 : b;
;         const float* src = r < CL ? p.in[2] + ((size_t)b * CL + r) * DM : p.in[0] + ((size_t)b * TL + (r - CL)) * DM;
;         const float* sh = mod + (size_t)s * 12288; const float* sc = sh + 2048;
.LBB0_469:
	s_or_b64 exec, exec, s[0:1]
	s_lshl_b32 s86, s26, 3
	s_lshl_b32 s88, s33, 3
	s_add_u32 s94, s50, 0xcba0000
	s_addc_u32 s95, s51, 0
	s_add_u32 s0, s50, 0x23ca0000
	v_mov_b32_e32 v1, v202
	s_addc_u32 s1, s51, 0
	s_waitcnt lgkmcnt(0)
	s_barrier
	v_writelane_b32 v253, s0, 7
	v_writelane_b32 v253, s1, 8
	v_and_b32_e32 v80, 63, v202
	v_lshrrev_b32_e32 v81, 6, v202
	v_lshlrev_b32_e32 v76, 4, v80
	v_lshlrev_b32_e32 v78, 3, v80
	v_readfirstlane_b32 s35, v81
	v_add_u32_e32 v77, 0x1000, v76
	s_lshl_b32 s9, s26, 3
	s_lshl_b32 s11, s33, 3
	s_nop 0
	s_add_u32 s9, s9, s35
.Lix_row:
	s_cmpk_ge_u32 s9, 0x2400
	s_cbranch_scc1 .Lix_done
	s_lshr_b32 s35, s9, 8
	s_mul_i32 s27, s35, 57
	s_lshr_b32 s27, s27, 9
	s_mul_i32 s35, s27, 0x900
	s_sub_u32 s29, s9, s35
	s_cmpk_lt_u32 s29, 0x100
	s_cbranch_scc1 .Lix_ctxrow
	s_lshl_b32 s35, s27, 11
	s_add_u32 s35, s35, s29
	s_sub_u32 s35, s35, 0x100
	s_lshl_b32 s35, s35, 13
	s_add_u32 s22, s68, s35
	s_addc_u32 s23, s69, 0
	s_mov_b32 s32, s27
	s_branch .Lix_go
.Lix_ctxrow:
	s_lshl_b32 s35, s27, 8
	s_add_u32 s35, s35, s29
	s_lshl_b32 s35, s35, 13
	s_add_u32 s22, s72, s35
	s_addc_u32 s23, s73, 0
	s_mov_b32 s32, 4
; DI void st_bf16x4(bf16_t* p, f32x4 v) { u32x2 w; w.x = cvt_pk_bf16(v[0], v[1]); w.y = cvt_pk_bf16(v[2], v[3]); *(u32x2*)p = w; }
; DI void phase_init_x(const Params& p) {
;     ...
;     for (int row = gw; row < MR; row += nw) {
;         const int b = row / RB, r = row % RB; const int s = r < CL ? 4 : b;
;         const float* src = r < CL ? p.in[2] + ((size_t)b * CL + r) * DM : p.in[0] + ((size_t)b * TL + (r - CL)) * DM;
;         const float* sh = mod + (size_t)s * 12288; const float* sc = sh + 2048;
; #pragma unroll
;         for (int i = 0; i < 8; ++i) {
;             const int col = (i * 64 + lane) * 4;
;             const f32x4 v = *(const f32x4*)(src + col);
;             *(f32x4*)(X + (size_t)row * DM + col) = v;
;             const f32x4 s4 = *(const f32x4*)(sh + col), c4 = *(const f32x4*)(sc + col);
;             st_bf16x4(H + (size_t)row * DM + col, v * (c4 + 1.f) + s4);
;         }
.Lix_go:
	global_load_dwordx4 v[88:91], v76, s[22:23] offset:0
	global_load_dwordx4 v[92:95], v76, s[22:23] offset:1024
	global_load_dwordx4 v[96:99], v76, s[22:23] offset:2048
	global_load_dwordx4 v[100:103], v76, s[22:23] offset:3072
	global_load_dwordx4 v[104:107], v77, s[22:23] offset:0
	global_load_dwordx4 v[108:111], v77, s[22:23] offset:1024
	global_load_dwordx4 v[112:115], v77, s[22:23] offset:2048
	global_load_dwordx4 v[116:119], v77, s[22:23] offset:3072
	s_mul_i32 s35, s32, 0xc000
	s_add_u32 s4, s50, 0x8000
	s_addc_u32 s5, s51, 0
	s_add_u32 s4, s4, s35
	s_addc_u32 s5, s5, 0
	global_load_dwordx4 v[140:143], v76, s[4:5] offset:0
	global_load_dwordx4 v[144:147], v76, s[4:5] offset:1024
	global_load_dwordx4 v[148:151], v76, s[4:5] offset:2048
	global_load_dwordx4 v[152:155], v76, s[4:5] offset:3072
	global_load_dwordx4 v[156:159], v77, s[4:5] offset:0
	global_load_dwordx4 v[160:163], v77, s[4:5] offset:1024
	global_load_dwordx4 v[164:167], v77, s[4:5] offset:2048
	global_load_dwordx4 v[168:171], v77, s[4:5] offset:3072
	s_add_u32 s4, s4, 0x2000
	s_addc_u32 s5, s5, 0
	global_load_dwordx4 v[204:207], v76, s[4:5] offset:0
	global_load_dwordx4 v[208:211], v76, s[4:5] offset:1024
	global_load_dwordx4 v[212:215], v76, s[4:5] offset:2048
	global_load_dwordx4 v[216:219], v76, s[4:5] offset:3072
	global_load_dwordx4 v[220:223], v77, s[4:5] offset:0
	global_load_dwordx4 v[224:227], v77, s[4:5] offset:1024
	global_load_dwordx4 v[228:231], v77, s[4:5] offset:2048
	global_load_dwordx4 v[232:235], v77, s[4:5] offset:3072
	s_lshl_b32 s35, s9, 13
	s_add_u32 s2, s50, 0xcba0000
	s_addc_u32 s3, s51, 0
	s_add_u32 s2, s2, s35
	s_addc_u32 s3, s3, 0
	s_lshl_b32 s35, s9, 12
	s_add_u32 s6, s50, 0x23ca0000
	s_addc_u32 s7, s51, 0
	s_add_u32 s6, s6, s35
	s_addc_u32 s7, s7, 0
	s_waitcnt vmcnt(16)
	global_store_dwordx4 v76, v[88:91], s[2:3] offset:0
	global_store_dwordx4 v76, v[92:95], s[2:3] offset:1024
	global_store_dwordx4 v76, v[96:99], s[2:3] offset:2048
	global_store_dwordx4 v76, v[100:103], s[2:3] offset:3072
	global_store_dwordx4 v77, v[104:107], s[2:3] offset:0
	global_store_dwordx4 v77, v[108:111], s[2:3] offset:1024
	global_store_dwordx4 v77, v[112:115], s[2:3] offset:2048
	global_store_dwordx4 v77, v[116:119], s[2:3] offset:3072
	s_waitcnt vmcnt(8)
	v_add_f32_e32 v204, 1.0, v204
	v_add_f32_e32 v205, 1.0, v205
	v_add_f32_e32 v206, 1.0, v206
	v_add_f32_e32 v207, 1.0, v207
	v_fma_f32 v204, v88, v204, v140
	v_fma_f32 v205, v89, v205, v141
	v_fma_f32 v206, v90, v206, v142
	v_fma_f32 v207, v91, v207, v143
	v_cvt_pk_bf16_f32 v204, v204, v205
	v_cvt_pk_bf16_f32 v205, v206, v207
	global_store_dwordx2 v78, v[204:205], s[6:7] offset:0
	v_add_f32_e32 v208, 1.0, v208
	v_add_f32_e32 v209, 1.0, v209
	v_add_f32_e32 v210, 1.0, v210
	v_add_f32_e32 v211, 1.0, v211
	v_fma_f32 v208, v92, v208, v144
	v_fma_f32 v209, v93, v209, v145
	v_fma_f32 v210, v94, v210, v146
	v_fma_f32 v211, v95, v211, v147
	v_cvt_pk_bf16_f32 v208, v208, v209
	v_cvt_pk_bf16_f32 v209, v210, v211
	global_store_dwordx2 v78, v[208:209], s[6:7] offset:512
	v_add_f32_e32 v212, 1.0, v212
	v_add_f32_e32 v213, 1.0, v213
	v_add_f32_e32 v214, 1.0, v214
	v_add_f32_e32 v215, 1.0, v215
	v_fma_f32 v212, v96, v212, v148
	v_fma_f32 v213, v97, v213, v149
	v_fma_f32 v214, v98, v214, v150
	v_fma_f32 v215, v99, v215, v151
	v_cvt_pk_bf16_f32 v212, v212, v213
	v_cvt_pk_bf16_f32 v213, v214, v215
	global_store_dwordx2 v78, v[212:213], s[6:7] offset:1024
	v_add_f32_e32 v216, 1.0, v216
	v_add_f32_e32 v217, 1.0, v217
	v_add_f32_e32 v218, 1.0, v218
	v_add_f32_e32 v219, 1.0, v219
	v_fma_f32 v216, v100, v216, v152
	v_fma_f32 v217, v101, v217, v153
	v_fma_f32 v218, v102, v218, v154
	v_fma_f32 v219, v103, v219, v155
	v_cvt_pk_bf16_f32 v216, v216, v217
	v_cvt_pk_bf16_f32 v217, v218, v219
	global_store_dwordx2 v78, v[216:217], s[6:7] offset:1536
	v_add_f32_e32 v220, 1.0, v220
	v_add_f32_e32 v221, 1.0, v221
	v_add_f32_e32 v222, 1.0, v222
	v_add_f32_e32 v223, 1.0, v223
	v_fma_f32 v220, v104, v220, v156
	v_fma_f32 v221, v105, v221, v157
	v_fma_f32 v222, v106, v222, v158
	v_fma_f32 v223, v107, v223, v159
	v_cvt_pk_bf16_f32 v220, v220, v221
	v_cvt_pk_bf16_f32 v221, v222, v223
	global_store_dwordx2 v78, v[220:221], s[6:7] offset:2048
	v_add_f32_e32 v224, 1.0, v224
	v_add_f32_e32 v225, 1.0, v225
	v_add_f32_e32 v226, 1.0, v226
	v_add_f32_e32 v227, 1.0, v227
	v_fma_f32 v224, v108, v224, v160
	v_fma_f32 v225, v109, v225, v161
	v_fma_f32 v226, v110, v226, v162
	v_fma_f32 v227, v111, v227, v163
	v_cvt_pk_bf16_f32 v224, v224, v225
	v_cvt_pk_bf16_f32 v225, v226, v227
	global_store_dwordx2 v78, v[224:225], s[6:7] offset:2560
	v_add_f32_e32 v228, 1.0, v228
	v_add_f32_e32 v229, 1.0, v229
	v_add_f32_e32 v230, 1.0, v230
	v_add_f32_e32 v231, 1.0, v231
	v_fma_f32 v228, v112, v228, v164
	v_fma_f32 v229, v113, v229, v165
	v_fma_f32 v230, v114, v230, v166
	v_fma_f32 v231, v115, v231, v167
	v_cvt_pk_bf16_f32 v228, v228, v229
	v_cvt_pk_bf16_f32 v229, v230, v231
	global_store_dwordx2 v78, v[228:229], s[6:7] offset:3072
	v_add_f32_e32 v232, 1.0, v232
	v_add_f32_e32 v233, 1.0, v233
	v_add_f32_e32 v234, 1.0, v234
	v_add_f32_e32 v235, 1.0, v235
	v_fma_f32 v232, v116, v232, v168
	v_fma_f32 v233, v117, v233, v169
	v_fma_f32 v234, v118, v234, v170
	v_fma_f32 v235, v119, v235, v171
	v_cvt_pk_bf16_f32 v232, v232, v233
	v_cvt_pk_bf16_f32 v233, v234, v235
	global_store_dwordx2 v78, v[232:233], s[6:7] offset:3584
	s_add_u32 s9, s9, s11
	s_branch .Lix_row
.Lix_done:
	s_waitcnt vmcnt(0)
	s_barrier
	s_and_saveexec_b64 s[0:1], s[24:25]
	s_cbranch_execz .LBB0_524
	s_add_i32 s2, 0, 0x22000
	v_mov_b32_e32 v0, s2
	s_waitcnt vmcnt(0) expcnt(0) lgkmcnt(0)
	ds_read_b32 v2, v0
	s_add_i32 s2, 0, 0x22004
	v_mov_b32_e32 v0, s2
	ds_read_b32 v0, v0
	s_waitcnt lgkmcnt(1)
	v_cmp_ne_u32_e32 vcc, 0, v2
	s_cbranch_vccnz .LBB0_488
	s_add_u32 s2, s50, 0x1000
	s_addc_u32 s3, s51, 0
	s_add_u32 s4, s50, 0x1100
	s_addc_u32 s5, s51, 0
	s_add_u32 s6, s50, 0x1200
	s_addc_u32 s7, s51, 0
	s_add_u32 s8, s50, 0x1300
	s_addc_u32 s9, s51, 0
	s_mov_b32 s16, 1
	v_mov_b32_e32 v16, 0
	s_branch .LBB0_476

; DI void phase_ln(const Params& p, const float* gam, const float* bet, const float* modnext  , bool skip_ctx, bool final_out,
;                  const float* cgate  , const float* pg, const float* pb  ) {
;     const int tid_ = otid(); const int lane = tid_ & 63, gw = blockIdx.x * 8 + (tid_ >> 6), nw = gridDim.x * 8;
;     float* X = (float*)(p.ws + WS_X); bf16_t* H = (bf16_t*)(p.ws + WS_H); float2* RS = (float2*)(p.ws + WS_RSTAT);
;     for (int rowA = gw; rowA < MR; rowA += 2 * nw) {
;         f32x4 v[2][8]; float sum[2] = {0.f, 0.f}; bool act[2]; int rows[2];
; #pragma unroll
;         for (int q = 0; q < 2; ++q) {
;             const int row = rowA + q * nw; rows[q] = row;
;             const int b = row / RB, r = row % RB;
;             act[q] = row < MR && !(skip_ctx && r < CL);
;             if (act[q]) {
;                 const bool cpart = cgate && r < CL;
;                 float pmu = 0.f, prs = 1.f;
;                 if (cpart && pg) { const float2 st = RS[row]; pmu = st.x; prs = st.y; }
; #pragma unroll
;                 for (int i = 0; i < 8; ++i) {
;                     const int col = (i * 64 + lane) * 4;
;                     v[q][i] = *(const f32x4*)(X + (size_t)row * DM + col);
;                     if (cpart) {
;                         if (pg) v[q][i] = (v[q][i] - pmu) * prs * *(const f32x4*)(pg + col) + *(const f32x4*)(pb + col);
;                         const float* pt = (const float*)(p.ws + WS_PART) + ((size_t)b * 256 + r) * DM + col;
;                         const f32x4 ps = *(const f32x4*)pt + *(const f32x4*)(pt + (size_t)1024 * DM) + *(const f32x4*)(pt + (size_t)2048 * DM) + *(const f32x4*)(pt + (size_t)3072 * DM);
;                         v[q][i] = v[q][i] * ALPHA + *(const f32x4*)(cgate + col) * ps;
;                         *(f32x4*)(X + (size_t)row * DM + col) = v[q][i];
;                     }
;                 }
;             } else {
; #pragma unroll
;                 for (int i = 0; i < 8; ++i) v[q][i] = (f32x4){0.f, 0.f, 0.f, 0.f};
;             }
;         }
; #pragma unroll
;         for (int q = 0; q < 2; ++q)
; #pragma unroll
;             for (int i = 0; i < 8; ++i) sum[q] += v[q][i][0] + v[q][i][1] + v[q][i][2] + v[q][i][3];
;         float mu[2], sq[2] = {0.f, 0.f}, rs[2];
; #pragma unroll
;         for (int o = 32; o > 0; o >>= 1) { sum[0] += __shfl_xor(sum[0], o); sum[1] += __shfl_xor(sum[1], o); }
.LBB0_1416:
	s_or_b64 exec, exec, s[6:7]
	s_add_u32 s2, s50, 0x260a0000
	s_waitcnt lgkmcnt(0)
	v_mov_b32_e32 v0, v202
	s_addc_u32 s3, s51, 0
	s_barrier
	v_writelane_b32 v253, s2, 17
	v_writelane_b32 v253, s3, 18
	v_and_b32_e32 v80, 63, v202
	v_lshrrev_b32_e32 v81, 6, v202
	v_lshlrev_b32_e32 v76, 4, v80
	v_lshlrev_b32_e32 v78, 3, v80
	v_readfirstlane_b32 s35, v81
	v_add_u32_e32 v77, 0x1000, v76
	v_mov_b32_e32 v79, 0
	s_lshl_b32 s9, s26, 3
	s_lshl_b32 s11, s33, 3
	s_nop 0
	s_add_u32 s9, s9, s35
	s_mov_b32 s82, 0x3a000000
	s_mov_b32 s83, 0x3727c5ac
	s_mov_b32 s89, 0x3fb504f3
	s_add_u32 s22, s64, 0x0
	s_addc_u32 s23, s65, 0
	global_load_dwordx4 v[12:15], v76, s[22:23] offset:0
	global_load_dwordx4 v[16:19], v76, s[22:23] offset:1024
	global_load_dwordx4 v[20:23], v76, s[22:23] offset:2048
	global_load_dwordx4 v[24:27], v76, s[22:23] offset:3072
	global_load_dwordx4 v[28:31], v77, s[22:23] offset:0
	global_load_dwordx4 v[32:35], v77, s[22:23] offset:1024
	global_load_dwordx4 v[36:39], v77, s[22:23] offset:2048
	global_load_dwordx4 v[40:43], v77, s[22:23] offset:3072
	s_add_u32 s22, s66, 0x0
	s_addc_u32 s23, s67, 0
	global_load_dwordx4 v[44:47], v76, s[22:23] offset:0
	global_load_dwordx4 v[48:51], v76, s[22:23] offset:1024
	global_load_dwordx4 v[52:55], v76, s[22:23] offset:2048
	global_load_dwordx4 v[56:59], v76, s[22:23] offset:3072
	global_load_dwordx4 v[60:63], v77, s[22:23] offset:0
	global_load_dwordx4 v[64:67], v77, s[22:23] offset:1024
	global_load_dwordx4 v[68:71], v77, s[22:23] offset:2048
	global_load_dwordx4 v[72:75], v77, s[22:23] offset:3072
.Ll0a_row:
	s_cmpk_ge_u32 s9, 0x2400
	s_cbranch_scc1 .Ll0a_done
	s_lshr_b32 s35, s9, 8
	s_mul_i32 s27, s35, 57
	s_lshr_b32 s27, s27, 9
	s_mul_i32 s35, s27, 0x900
	s_sub_u32 s29, s9, s35
	s_cmpk_lt_u32 s29, 0x100
	s_cselect_b32 s32, 4, s27
	s_lshl_b32 s35, s9, 13
	s_add_u32 s2, s50, 0xcba0000
	s_addc_u32 s3, s51, 0
	s_add_u32 s2, s2, s35
	s_addc_u32 s3, s3, 0
	global_load_dwordx4 v[88:91], v76, s[2:3] offset:0
	global_load_dwordx4 v[92:95], v76, s[2:3] offset:1024
	global_load_dwordx4 v[96:99], v76, s[2:3] offset:2048
	global_load_dwordx4 v[100:103], v76, s[2:3] offset:3072
	global_load_dwordx4 v[104:107], v77, s[2:3] offset:0
	global_load_dwordx4 v[108:111], v77, s[2:3] offset:1024
	global_load_dwordx4 v[112:115], v77, s[2:3] offset:2048
	global_load_dwordx4 v[116:119], v77, s[2:3] offset:3072
	s_cmpk_lt_u32 s29, 0x100
	s_cbranch_scc1 .Ll0a_cpart
.Ll0a_cpart_done:
	s_mul_i32 s35, s32, 0xc000
	s_add_u32 s4, s50, 0xe000
	s_addc_u32 s5, s51, 0
	s_add_u32 s4, s4, s35
	s_addc_u32 s5, s5, 0
	global_load_dwordx4 v[140:143], v76, s[4:5] offset:0
	global_load_dwordx4 v[144:147], v76, s[4:5] offset:1024
	global_load_dwordx4 v[148:151], v76, s[4:5] offset:2048
	global_load_dwordx4 v[152:155], v76, s[4:5] offset:3072
	global_load_dwordx4 v[156:159], v77, s[4:5] offset:0
	global_load_dwordx4 v[160:163], v77, s[4:5] offset:1024
	global_load_dwordx4 v[164:167], v77, s[4:5] offset:2048
	global_load_dwordx4 v[168:171], v77, s[4:5] offset:3072
	s_add_u32 s4, s4, 0x2000
	s_addc_u32 s5, s5, 0
	global_load_dwordx4 v[204:207], v76, s[4:5] offset:0
	global_load_dwordx4 v[208:211], v76, s[4:5] offset:1024
	global_load_dwordx4 v[212:215], v76, s[4:5] offset:2048
	global_load_dwordx4 v[216:219], v76, s[4:5] offset:3072
	global_load_dwordx4 v[220:223], v77, s[4:5] offset:0
	global_load_dwordx4 v[224:227], v77, s[4:5] offset:1024
	global_load_dwordx4 v[228:231], v77, s[4:5] offset:2048
	global_load_dwordx4 v[232:235], v77, s[4:5] offset:3072
	s_waitcnt vmcnt(16)
	v_add_f32_e32 v80, v88, v92
	v_add_f32_e32 v81, v89, v93
	v_add_f32_e32 v82, v90, v94
	v_add_f32_e32 v83, v91, v95
	v_add_f32_e32 v80, v96, v80
	v_add_f32_e32 v81, v97, v81
	v_add_f32_e32 v82, v98, v82
	v_add_f32_e32 v83, v99, v83
	v_add_f32_e32 v80, v100, v80
	v_add_f32_e32 v81, v101, v81
	v_add_f32_e32 v82, v102, v82
	v_add_f32_e32 v83, v103, v83
	v_add_f32_e32 v80, v104, v80
	v_add_f32_e32 v81, v105, v81
	v_add_f32_e32 v82, v106, v82
	v_add_f32_e32 v83, v107, v83
	v_add_f32_e32 v80, v108, v80
	v_add_f32_e32 v81, v109, v81
	v_add_f32_e32 v82, v110, v82
	v_add_f32_e32 v83, v111, v83
	v_add_f32_e32 v80, v112, v80
	v_add_f32_e32 v81, v113, v81
	v_add_f32_e32 v82, v114, v82
	v_add_f32_e32 v83, v115, v83
	v_add_f32_e32 v80, v116, v80
	v_add_f32_e32 v81, v117, v81
	v_add_f32_e32 v82, v118, v82
	v_add_f32_e32 v83, v119, v83
	v_add_f32_e32 v80, v80, v81
	v_add_f32_e32 v82, v82, v83
	v_add_f32_e32 v80, v80, v82
	s_nop 1
	v_add_f32_dpp v86, v80, v80 quad_perm:[1,0,3,2] row_mask:0xf bank_mask:0xf
	s_nop 1
	v_add_f32_dpp v86, v86, v86 quad_perm:[2,3,0,1] row_mask:0xf bank_mask:0xf
	s_nop 1
	v_add_f32_dpp v86, v86, v86 row_half_mirror row_mask:0xf bank_mask:0xf
	s_nop 1
	v_add_f32_dpp v86, v86, v86 row_mirror row_mask:0xf bank_mask:0xf
	s_nop 1
	v_readlane_b32 s69, v86, 0
	v_readlane_b32 s71, v86, 16
	v_readlane_b32 s73, v86, 32
	v_readlane_b32 s81, v86, 48
	s_nop 3
	v_mov_b32_e32 v84, s69
	v_add_f32_e32 v84, s71, v84
	v_add_f32_e32 v84, s73, v84
	v_add_f32_e32 v84, s81, v84
	v_mul_f32_e32 v236, s82, v84
	v_sub_f32_e32 v88, v88, v236
	v_sub_f32_e32 v89, v89, v236
	v_sub_f32_e32 v90, v90, v236
	v_sub_f32_e32 v91, v91, v236
	v_sub_f32_e32 v92, v92, v236
	v_sub_f32_e32 v93, v93, v236
	v_sub_f32_e32 v94, v94, v236
	v_sub_f32_e32 v95, v95, v236
	v_sub_f32_e32 v96, v96, v236
	v_sub_f32_e32 v97, v97, v236
	v_sub_f32_e32 v98, v98, v236
	v_sub_f32_e32 v99, v99, v236
	v_sub_f32_e32 v100, v100, v236
	v_sub_f32_e32 v101, v101, v236
	v_sub_f32_e32 v102, v102, v236
	v_sub_f32_e32 v103, v103, v236
	v_sub_f32_e32 v104, v104, v236
	v_sub_f32_e32 v105, v105, v236
	v_sub_f32_e32 v106, v106, v236
; DI void st_bf16x4(bf16_t* p, f32x4 v) { u32x2 w; w.x = cvt_pk_bf16(v[0], v[1]); w.y = cvt_pk_bf16(v[2], v[3]); *(u32x2*)p = w; }
; DI void phase_ln(const Params& p, const float* gam, const float* bet, const float* modnext  , bool skip_ctx, bool final_out,
;                  const float* cgate  , const float* pg, const float* pb  ) {
;     ...
;             for (int i = 0; i < 8; ++i) { v[q][i] -= mu[q]; sq[q] += v[q][i][0] * v[q][i][0] + v[q][i][1] * v[q][i][1] + v[q][i][2] * v[q][i][2] + v[q][i][3] * v[q][i][3]; }
;         }
; #pragma unroll
;         for (int o = 32; o > 0; o >>= 1) { sq[0] += __shfl_xor(sq[0], o); sq[1] += __shfl_xor(sq[1], o); }
; #pragma unroll
;         for (int q = 0; q < 2; ++q) {
;             if (!act[q]) continue;
;             rs[q] = rsqrtf(sq[q] * (1.f / 2048.f) + 1e-5f);
;             const int row = rows[q]; const int b = row / RB, r = row % RB; const int s = r < CL ? 4 : b;
;             if (lane == 0 && !final_out) RS[row] = make_float2(mu[q], rs[q]);
; #pragma unroll
;             for (int i = 0; i < 8; ++i) {
;                 const int col = (i * 64 + lane) * 4;
;                 const f32x4 o = v[q][i] * rs[q] * *(const f32x4*)(gam + col) + *(const f32x4*)(bet + col);
;                 if (final_out) { *(f32x4*)(p.out + ((size_t)b * TL + (r - CL)) * DM + col) = o; }
;                 else {
;                     const f32x4 s4 = *(const f32x4*)(modnext + (size_t)s * 12288 + col), c4 = *(const f32x4*)(modnext + (size_t)s * 12288 + 2048 + col);
;                     st_bf16x4(H + (size_t)row * DM + col, o * (c4 + 1.f) + s4);
	v_sub_f32_e32 v107, v107, v236
	v_sub_f32_e32 v108, v108, v236
	v_sub_f32_e32 v109, v109, v236
	v_sub_f32_e32 v110, v110, v236
	v_sub_f32_e32 v111, v111, v236
	v_sub_f32_e32 v112, v112, v236
	v_sub_f32_e32 v113, v113, v236
	v_sub_f32_e32 v114, v114, v236
	v_sub_f32_e32 v115, v115, v236
	v_sub_f32_e32 v116, v116, v236
	v_sub_f32_e32 v117, v117, v236
	v_sub_f32_e32 v118, v118, v236
	v_sub_f32_e32 v119, v119, v236
	v_mul_f32_e32 v80, v88, v88
	v_mul_f32_e32 v81, v89, v89
	v_mul_f32_e32 v82, v90, v90
	v_mul_f32_e32 v83, v91, v91
	v_fmac_f32_e32 v80, v92, v92
	v_fmac_f32_e32 v81, v93, v93
	v_fmac_f32_e32 v82, v94, v94
	v_fmac_f32_e32 v83, v95, v95
	v_fmac_f32_e32 v80, v96, v96
	v_fmac_f32_e32 v81, v97, v97
	v_fmac_f32_e32 v82, v98, v98
	v_fmac_f32_e32 v83, v99, v99
	v_fmac_f32_e32 v80, v100, v100
	v_fmac_f32_e32 v81, v101, v101
	v_fmac_f32_e32 v82, v102, v102
	v_fmac_f32_e32 v83, v103, v103
	v_fmac_f32_e32 v80, v104, v104
	v_fmac_f32_e32 v81, v105, v105
	v_fmac_f32_e32 v82, v106, v106
	v_fmac_f32_e32 v83, v107, v107
	v_fmac_f32_e32 v80, v108, v108
	v_fmac_f32_e32 v81, v109, v109
	v_fmac_f32_e32 v82, v110, v110
	v_fmac_f32_e32 v83, v111, v111
	v_fmac_f32_e32 v80, v112, v112
	v_fmac_f32_e32 v81, v113, v113
	v_fmac_f32_e32 v82, v114, v114
	v_fmac_f32_e32 v83, v115, v115
	v_fmac_f32_e32 v80, v116, v116
	v_fmac_f32_e32 v81, v117, v117
	v_fmac_f32_e32 v82, v118, v118
	v_fmac_f32_e32 v83, v119, v119
	v_add_f32_e32 v80, v80, v81
	v_add_f32_e32 v82, v82, v83
	v_add_f32_e32 v80, v80, v82
	s_nop 1
	v_add_f32_dpp v86, v80, v80 quad_perm:[1,0,3,2] row_mask:0xf bank_mask:0xf
	s_nop 1
	v_add_f32_dpp v86, v86, v86 quad_perm:[2,3,0,1] row_mask:0xf bank_mask:0xf
	s_nop 1
	v_add_f32_dpp v86, v86, v86 row_half_mirror row_mask:0xf bank_mask:0xf
	s_nop 1
	v_add_f32_dpp v86, v86, v86 row_mirror row_mask:0xf bank_mask:0xf
	s_nop 1
	v_readlane_b32 s69, v86, 0
	v_readlane_b32 s71, v86, 16
	v_readlane_b32 s73, v86, 32
	v_readlane_b32 s81, v86, 48
	s_nop 3
	v_mov_b32_e32 v84, s69
	v_add_f32_e32 v84, s71, v84
	v_add_f32_e32 v84, s73, v84
	v_add_f32_e32 v84, s81, v84
	v_mov_b32_e32 v86, s83
	v_fmac_f32_e32 v86, s82, v84
	v_rsq_f32_e32 v237, v86
	s_nop 0
	s_lshl_b32 s35, s9, 3
	s_add_u32 s22, s50, 0x260a0000
	s_addc_u32 s23, s51, 0
	s_add_u32 s22, s22, s35
	s_addc_u32 s23, s23, 0
	s_mov_b64 s[74:75], exec
	s_mov_b64 exec, 1
	global_store_dwordx2 v79, v[236:237], s[22:23]
	s_mov_b64 exec, s[74:75]
	s_lshl_b32 s35, s9, 12
	s_add_u32 s6, s50, 0x23ca0000
	s_addc_u32 s7, s51, 0
	s_add_u32 s6, s6, s35
	s_addc_u32 s7, s7, 0
	s_waitcnt vmcnt(1)
	v_mul_f32_e32 v88, v88, v237
	v_mul_f32_e32 v89, v89, v237
	v_mul_f32_e32 v90, v90, v237
	v_mul_f32_e32 v91, v91, v237
	v_fma_f32 v88, v88, v12, v44
	v_fma_f32 v89, v89, v13, v45
	v_fma_f32 v90, v90, v14, v46
	v_fma_f32 v91, v91, v15, v47
	v_add_f32_e32 v204, 1.0, v204
	v_add_f32_e32 v205, 1.0, v205
	v_add_f32_e32 v206, 1.0, v206
	v_add_f32_e32 v207, 1.0, v207
	v_fma_f32 v88, v88, v204, v140
	v_fma_f32 v89, v89, v205, v141
	v_fma_f32 v90, v90, v206, v142
	v_fma_f32 v91, v91, v207, v143
	v_cvt_pk_bf16_f32 v88, v88, v89
	v_cvt_pk_bf16_f32 v89, v90, v91
	global_store_dwordx2 v78, v[88:89], s[6:7] offset:0
	v_mul_f32_e32 v92, v92, v237
	v_mul_f32_e32 v93, v93, v237
	v_mul_f32_e32 v94, v94, v237
	v_mul_f32_e32 v95, v95, v237
	v_fma_f32 v92, v92, v16, v48
	v_fma_f32 v93, v93, v17, v49
	v_fma_f32 v94, v94, v18, v50
	v_fma_f32 v95, v95, v19, v51
	v_add_f32_e32 v208, 1.0, v208
	v_add_f32_e32 v209, 1.0, v209
	v_add_f32_e32 v210, 1.0, v210
	v_add_f32_e32 v211, 1.0, v211
	v_fma_f32 v92, v92, v208, v144
	v_fma_f32 v93, v93, v209, v145
	v_fma_f32 v94, v94, v210, v146
	v_fma_f32 v95, v95, v211, v147
	v_cvt_pk_bf16_f32 v92, v92, v93
	v_cvt_pk_bf16_f32 v93, v94, v95
	global_store_dwordx2 v78, v[92:93], s[6:7] offset:512
	v_mul_f32_e32 v96, v96, v237
	v_mul_f32_e32 v97, v97, v237
	v_mul_f32_e32 v98, v98, v237
	v_mul_f32_e32 v99, v99, v237
	v_fma_f32 v96, v96, v20, v52
	v_fma_f32 v97, v97, v21, v53
	v_fma_f32 v98, v98, v22, v54
	v_fma_f32 v99, v99, v23, v55
	v_add_f32_e32 v212, 1.0, v212
	v_add_f32_e32 v213, 1.0, v213
	v_add_f32_e32 v214, 1.0, v214
	v_add_f32_e32 v215, 1.0, v215
	v_fma_f32 v96, v96, v212, v148
	v_fma_f32 v97, v97, v213, v149
	v_fma_f32 v98, v98, v214, v150
	v_fma_f32 v99, v99, v215, v151
	v_cvt_pk_bf16_f32 v96, v96, v97
	v_cvt_pk_bf16_f32 v97, v98, v99
	global_store_dwordx2 v78, v[96:97], s[6:7] offset:1024
	v_mul_f32_e32 v100, v100, v237
	v_mul_f32_e32 v101, v101, v237
	v_mul_f32_e32 v102, v102, v237
	v_mul_f32_e32 v103, v103, v237
	v_fma_f32 v100, v100, v24, v56
	v_fma_f32 v101, v101, v25, v57
	v_fma_f32 v102, v102, v26, v58
	v_fma_f32 v103, v103, v27, v59
	v_add_f32_e32 v216, 1.0, v216
	v_add_f32_e32 v217, 1.0, v217
	v_add_f32_e32 v218, 1.0, v218
	v_add_f32_e32 v219, 1.0, v219
	v_fma_f32 v100, v100, v216, v152
	v_fma_f32 v101, v101, v217, v153
	v_fma_f32 v102, v102, v218, v154
	v_fma_f32 v103, v103, v219, v155
	v_cvt_pk_bf16_f32 v100, v100, v101
	v_cvt_pk_bf16_f32 v101, v102, v103
	global_store_dwordx2 v78, v[100:101], s[6:7] offset:1536
	v_mul_f32_e32 v104, v104, v237
	v_mul_f32_e32 v105, v105, v237
	v_mul_f32_e32 v106, v106, v237
	v_mul_f32_e32 v107, v107, v237
	v_fma_f32 v104, v104, v28, v60
	v_fma_f32 v105, v105, v29, v61
	v_fma_f32 v106, v106, v30, v62
	v_fma_f32 v107, v107, v31, v63
	v_add_f32_e32 v220, 1.0, v220
	v_add_f32_e32 v221, 1.0, v221
	v_add_f32_e32 v222, 1.0, v222
	v_add_f32_e32 v223, 1.0, v223
	v_fma_f32 v104, v104, v220, v156
	v_fma_f32 v105, v105, v221, v157
	v_fma_f32 v106, v106, v222, v158
	v_fma_f32 v107, v107, v223, v159
	v_cvt_pk_bf16_f32 v104, v104, v105
	v_cvt_pk_bf16_f32 v105, v106, v107
; DI void st_bf16x4(bf16_t* p, f32x4 v) { u32x2 w; w.x = cvt_pk_bf16(v[0], v[1]); w.y = cvt_pk_bf16(v[2], v[3]); *(u32x2*)p = w; }
; DI void phase_ln(const Params& p, const float* gam, const float* bet, const float* modnext  , bool skip_ctx, bool final_out,
;                  const float* cgate  , const float* pg, const float* pb  ) {
;     ...
;                     if (cpart) {
;                         if (pg) v[q][i] = (v[q][i] - pmu) * prs * *(const f32x4*)(pg + col) + *(const f32x4*)(pb + col);
;                         const float* pt = (const float*)(p.ws + WS_PART) + ((size_t)b * 256 + r) * DM + col;
;                         const f32x4 ps = *(const f32x4*)pt + *(const f32x4*)(pt + (size_t)1024 * DM) + *(const f32x4*)(pt + (size_t)2048 * DM) + *(const f32x4*)(pt + (size_t)3072 * DM);
;                         v[q][i] = v[q][i] * ALPHA + *(const f32x4*)(cgate + col) * ps;
;                         *(f32x4*)(X + (size_t)row * DM + col) = v[q][i];
;     ...
;             for (int i = 0; i < 8; ++i) {
;                 const int col = (i * 64 + lane) * 4;
;                 const f32x4 o = v[q][i] * rs[q] * *(const f32x4*)(gam + col) + *(const f32x4*)(bet + col);
;                 if (final_out) { *(f32x4*)(p.out + ((size_t)b * TL + (r - CL)) * DM + col) = o; }
;                 else {
;                     const f32x4 s4 = *(const f32x4*)(modnext + (size_t)s * 12288 + col), c4 = *(const f32x4*)(modnext + (size_t)s * 12288 + 2048 + col);
;                     st_bf16x4(H + (size_t)row * DM + col, o * (c4 + 1.f) + s4);
	global_store_dwordx2 v78, v[104:105], s[6:7] offset:2048
	v_mul_f32_e32 v108, v108, v237
	v_mul_f32_e32 v109, v109, v237
	v_mul_f32_e32 v110, v110, v237
	v_mul_f32_e32 v111, v111, v237
	v_fma_f32 v108, v108, v32, v64
	v_fma_f32 v109, v109, v33, v65
	v_fma_f32 v110, v110, v34, v66
	v_fma_f32 v111, v111, v35, v67
	v_add_f32_e32 v224, 1.0, v224
	v_add_f32_e32 v225, 1.0, v225
	v_add_f32_e32 v226, 1.0, v226
	v_add_f32_e32 v227, 1.0, v227
	v_fma_f32 v108, v108, v224, v160
	v_fma_f32 v109, v109, v225, v161
	v_fma_f32 v110, v110, v226, v162
	v_fma_f32 v111, v111, v227, v163
	v_cvt_pk_bf16_f32 v108, v108, v109
	v_cvt_pk_bf16_f32 v109, v110, v111
	global_store_dwordx2 v78, v[108:109], s[6:7] offset:2560
	v_mul_f32_e32 v112, v112, v237
	v_mul_f32_e32 v113, v113, v237
	v_mul_f32_e32 v114, v114, v237
	v_mul_f32_e32 v115, v115, v237
	v_fma_f32 v112, v112, v36, v68
	v_fma_f32 v113, v113, v37, v69
	v_fma_f32 v114, v114, v38, v70
	v_fma_f32 v115, v115, v39, v71
	v_add_f32_e32 v228, 1.0, v228
	v_add_f32_e32 v229, 1.0, v229
	v_add_f32_e32 v230, 1.0, v230
	v_add_f32_e32 v231, 1.0, v231
	v_fma_f32 v112, v112, v228, v164
	v_fma_f32 v113, v113, v229, v165
	v_fma_f32 v114, v114, v230, v166
	v_fma_f32 v115, v115, v231, v167
	v_cvt_pk_bf16_f32 v112, v112, v113
	v_cvt_pk_bf16_f32 v113, v114, v115
	global_store_dwordx2 v78, v[112:113], s[6:7] offset:3072
	v_mul_f32_e32 v116, v116, v237
	v_mul_f32_e32 v117, v117, v237
	v_mul_f32_e32 v118, v118, v237
	v_mul_f32_e32 v119, v119, v237
	v_fma_f32 v116, v116, v40, v72
	v_fma_f32 v117, v117, v41, v73
	v_fma_f32 v118, v118, v42, v74
	v_fma_f32 v119, v119, v43, v75
	v_add_f32_e32 v232, 1.0, v232
	v_add_f32_e32 v233, 1.0, v233
	v_add_f32_e32 v234, 1.0, v234
	v_add_f32_e32 v235, 1.0, v235
	v_fma_f32 v116, v116, v232, v168
	v_fma_f32 v117, v117, v233, v169
	v_fma_f32 v118, v118, v234, v170
	v_fma_f32 v119, v119, v235, v171
	v_cvt_pk_bf16_f32 v116, v116, v117
	v_cvt_pk_bf16_f32 v117, v118, v119
	global_store_dwordx2 v78, v[116:117], s[6:7] offset:3584
.Ll0a_next:
	s_add_u32 s9, s9, s11
	s_branch .Ll0a_row
.Ll0a_cpart:
	s_lshl_b32 s35, s27, 8
	s_add_u32 s35, s35, s29
	s_lshl_b32 s35, s35, 13
	s_add_u32 s4, s50, 0x123a0000
	s_addc_u32 s5, s51, 0
	s_add_u32 s4, s4, s35
	s_addc_u32 s5, s5, 0
	global_load_dwordx4 v[140:143], v76, s[4:5] offset:0
	global_load_dwordx4 v[144:147], v76, s[4:5] offset:1024
	s_add_u32 s4, s4, 0x800000
	s_addc_u32 s5, s5, 0
	global_load_dwordx4 v[148:151], v76, s[4:5] offset:0
	global_load_dwordx4 v[152:155], v76, s[4:5] offset:1024
	s_add_u32 s4, s4, 0x800000
	s_addc_u32 s5, s5, 0
	global_load_dwordx4 v[156:159], v76, s[4:5] offset:0
	global_load_dwordx4 v[160:163], v76, s[4:5] offset:1024
	s_add_u32 s4, s4, 0x800000
	s_addc_u32 s5, s5, 0
	global_load_dwordx4 v[164:167], v76, s[4:5] offset:0
	global_load_dwordx4 v[168:171], v76, s[4:5] offset:1024
	s_sub_u32 s4, s4, 0x1800000
	s_subb_u32 s5, s5, 0
	s_add_u32 s22, s50, 0x3c000
	s_addc_u32 s23, s51, 0
	global_load_dwordx4 v[204:207], v76, s[22:23] offset:0
	global_load_dwordx4 v[208:211], v76, s[22:23] offset:1024
	s_waitcnt vmcnt(0)
	v_add_f32_e32 v140, v140, v148
	v_add_f32_e32 v140, v140, v156
	v_add_f32_e32 v140, v140, v164
	v_mul_f32_e32 v140, v204, v140
	v_fmac_f32_e32 v140, s89, v88
	v_mov_b32_e32 v88, v140
	v_add_f32_e32 v141, v141, v149
	v_add_f32_e32 v141, v141, v157
	v_add_f32_e32 v141, v141, v165
	v_mul_f32_e32 v141, v205, v141
	v_fmac_f32_e32 v141, s89, v89
	v_mov_b32_e32 v89, v141
	v_add_f32_e32 v142, v142, v150
	v_add_f32_e32 v142, v142, v158
	v_add_f32_e32 v142, v142, v166
	v_mul_f32_e32 v142, v206, v142
	v_fmac_f32_e32 v142, s89, v90
	v_mov_b32_e32 v90, v142
	v_add_f32_e32 v143, v143, v151
	v_add_f32_e32 v143, v143, v159
	v_add_f32_e32 v143, v143, v167
	v_mul_f32_e32 v143, v207, v143
	v_fmac_f32_e32 v143, s89, v91
	v_mov_b32_e32 v91, v143
	global_store_dwordx4 v76, v[88:91], s[2:3] offset:0
	v_add_f32_e32 v144, v144, v152
	v_add_f32_e32 v144, v144, v160
	v_add_f32_e32 v144, v144, v168
	v_mul_f32_e32 v144, v208, v144
	v_fmac_f32_e32 v144, s89, v92
	v_mov_b32_e32 v92, v144
	v_add_f32_e32 v145, v145, v153
	v_add_f32_e32 v145, v145, v161
	v_add_f32_e32 v145, v145, v169
	v_mul_f32_e32 v145, v209, v145
	v_fmac_f32_e32 v145, s89, v93
	v_mov_b32_e32 v93, v145
	v_add_f32_e32 v146, v146, v154
	v_add_f32_e32 v146, v146, v162
	v_add_f32_e32 v146, v146, v170
	v_mul_f32_e32 v146, v210, v146
	v_fmac_f32_e32 v146, s89, v94
	v_mov_b32_e32 v94, v146
	v_add_f32_e32 v147, v147, v155
	v_add_f32_e32 v147, v147, v163
	v_add_f32_e32 v147, v147, v171
	v_mul_f32_e32 v147, v211, v147
	v_fmac_f32_e32 v147, s89, v95
	v_mov_b32_e32 v95, v147
	global_store_dwordx4 v76, v[92:95], s[2:3] offset:1024
	global_load_dwordx4 v[140:143], v76, s[4:5] offset:2048
	global_load_dwordx4 v[144:147], v76, s[4:5] offset:3072
	s_add_u32 s4, s4, 0x800000
	s_addc_u32 s5, s5, 0
	global_load_dwordx4 v[148:151], v76, s[4:5] offset:2048
	global_load_dwordx4 v[152:155], v76, s[4:5] offset:3072
	s_add_u32 s4, s4, 0x800000
	s_addc_u32 s5, s5, 0
	global_load_dwordx4 v[156:159], v76, s[4:5] offset:2048
	global_load_dwordx4 v[160:163], v76, s[4:5] offset:3072
	s_add_u32 s4, s4, 0x800000
	s_addc_u32 s5, s5, 0
	global_load_dwordx4 v[164:167], v76, s[4:5] offset:2048
	global_load_dwordx4 v[168:171], v76, s[4:5] offset:3072
	s_sub_u32 s4, s4, 0x1800000
	s_subb_u32 s5, s5, 0
	s_add_u32 s22, s50, 0x3c000
	s_addc_u32 s23, s51, 0
	global_load_dwordx4 v[204:207], v76, s[22:23] offset:2048
	global_load_dwordx4 v[208:211], v76, s[22:23] offset:3072
	s_waitcnt vmcnt(0)
; DI void phase_ln(const Params& p, const float* gam, const float* bet, const float* modnext  , bool skip_ctx, bool final_out,
;                  const float* cgate  , const float* pg, const float* pb  ) {
;     ...
;                     if (cpart) {
;                         if (pg) v[q][i] = (v[q][i] - pmu) * prs * *(const f32x4*)(pg + col) + *(const f32x4*)(pb + col);
;                         const float* pt = (const float*)(p.ws + WS_PART) + ((size_t)b * 256 + r) * DM + col;
;                         const f32x4 ps = *(const f32x4*)pt + *(const f32x4*)(pt + (size_t)1024 * DM) + *(const f32x4*)(pt + (size_t)2048 * DM) + *(const f32x4*)(pt + (size_t)3072 * DM);
;                         v[q][i] = v[q][i] * ALPHA + *(const f32x4*)(cgate + col) * ps;
;                         *(f32x4*)(X + (size_t)row * DM + col) = v[q][i];
	v_add_f32_e32 v140, v140, v148
	v_add_f32_e32 v140, v140, v156
	v_add_f32_e32 v140, v140, v164
	v_mul_f32_e32 v140, v204, v140
	v_fmac_f32_e32 v140, s89, v96
	v_mov_b32_e32 v96, v140
	v_add_f32_e32 v141, v141, v149
	v_add_f32_e32 v141, v141, v157
	v_add_f32_e32 v141, v141, v165
	v_mul_f32_e32 v141, v205, v141
	v_fmac_f32_e32 v141, s89, v97
	v_mov_b32_e32 v97, v141
	v_add_f32_e32 v142, v142, v150
	v_add_f32_e32 v142, v142, v158
	v_add_f32_e32 v142, v142, v166
	v_mul_f32_e32 v142, v206, v142
	v_fmac_f32_e32 v142, s89, v98
	v_mov_b32_e32 v98, v142
	v_add_f32_e32 v143, v143, v151
	v_add_f32_e32 v143, v143, v159
	v_add_f32_e32 v143, v143, v167
	v_mul_f32_e32 v143, v207, v143
	v_fmac_f32_e32 v143, s89, v99
	v_mov_b32_e32 v99, v143
	global_store_dwordx4 v76, v[96:99], s[2:3] offset:2048
	v_add_f32_e32 v144, v144, v152
	v_add_f32_e32 v144, v144, v160
	v_add_f32_e32 v144, v144, v168
	v_mul_f32_e32 v144, v208, v144
	v_fmac_f32_e32 v144, s89, v100
	v_mov_b32_e32 v100, v144
	v_add_f32_e32 v145, v145, v153
	v_add_f32_e32 v145, v145, v161
	v_add_f32_e32 v145, v145, v169
	v_mul_f32_e32 v145, v209, v145
	v_fmac_f32_e32 v145, s89, v101
	v_mov_b32_e32 v101, v145
	v_add_f32_e32 v146, v146, v154
	v_add_f32_e32 v146, v146, v162
	v_add_f32_e32 v146, v146, v170
	v_mul_f32_e32 v146, v210, v146
	v_fmac_f32_e32 v146, s89, v102
	v_mov_b32_e32 v102, v146
	v_add_f32_e32 v147, v147, v155
	v_add_f32_e32 v147, v147, v163
	v_add_f32_e32 v147, v147, v171
	v_mul_f32_e32 v147, v211, v147
	v_fmac_f32_e32 v147, s89, v103
	v_mov_b32_e32 v103, v147
	global_store_dwordx4 v76, v[100:103], s[2:3] offset:3072
	global_load_dwordx4 v[140:143], v77, s[4:5] offset:0
	global_load_dwordx4 v[144:147], v77, s[4:5] offset:1024
	s_add_u32 s4, s4, 0x800000
	s_addc_u32 s5, s5, 0
	global_load_dwordx4 v[148:151], v77, s[4:5] offset:0
	global_load_dwordx4 v[152:155], v77, s[4:5] offset:1024
	s_add_u32 s4, s4, 0x800000
	s_addc_u32 s5, s5, 0
	global_load_dwordx4 v[156:159], v77, s[4:5] offset:0
	global_load_dwordx4 v[160:163], v77, s[4:5] offset:1024
	s_add_u32 s4, s4, 0x800000
	s_addc_u32 s5, s5, 0
	global_load_dwordx4 v[164:167], v77, s[4:5] offset:0
	global_load_dwordx4 v[168:171], v77, s[4:5] offset:1024
	s_sub_u32 s4, s4, 0x1800000
	s_subb_u32 s5, s5, 0
	s_add_u32 s22, s50, 0x3c000
	s_addc_u32 s23, s51, 0
	global_load_dwordx4 v[204:207], v77, s[22:23] offset:0
	global_load_dwordx4 v[208:211], v77, s[22:23] offset:1024
	s_waitcnt vmcnt(0)
	v_add_f32_e32 v140, v140, v148
	v_add_f32_e32 v140, v140, v156
	v_add_f32_e32 v140, v140, v164
	v_mul_f32_e32 v140, v204, v140
	v_fmac_f32_e32 v140, s89, v104
	v_mov_b32_e32 v104, v140
	v_add_f32_e32 v141, v141, v149
	v_add_f32_e32 v141, v141, v157
	v_add_f32_e32 v141, v141, v165
	v_mul_f32_e32 v141, v205, v141
	v_fmac_f32_e32 v141, s89, v105
	v_mov_b32_e32 v105, v141
	v_add_f32_e32 v142, v142, v150
	v_add_f32_e32 v142, v142, v158
	v_add_f32_e32 v142, v142, v166
	v_mul_f32_e32 v142, v206, v142
	v_fmac_f32_e32 v142, s89, v106
	v_mov_b32_e32 v106, v142
	v_add_f32_e32 v143, v143, v151
	v_add_f32_e32 v143, v143, v159
	v_add_f32_e32 v143, v143, v167
	v_mul_f32_e32 v143, v207, v143
	v_fmac_f32_e32 v143, s89, v107
	v_mov_b32_e32 v107, v143
	global_store_dwordx4 v77, v[104:107], s[2:3] offset:0
	v_add_f32_e32 v144, v144, v152
	v_add_f32_e32 v144, v144, v160
	v_add_f32_e32 v144, v144, v168
	v_mul_f32_e32 v144, v208, v144
	v_fmac_f32_e32 v144, s89, v108
	v_mov_b32_e32 v108, v144
	v_add_f32_e32 v145, v145, v153
	v_add_f32_e32 v145, v145, v161
	v_add_f32_e32 v145, v145, v169
	v_mul_f32_e32 v145, v209, v145
	v_fmac_f32_e32 v145, s89, v109
	v_mov_b32_e32 v109, v145
	v_add_f32_e32 v146, v146, v154
	v_add_f32_e32 v146, v146, v162
	v_add_f32_e32 v146, v146, v170
	v_mul_f32_e32 v146, v210, v146
	v_fmac_f32_e32 v146, s89, v110
	v_mov_b32_e32 v110, v146
	v_add_f32_e32 v147, v147, v155
	v_add_f32_e32 v147, v147, v163
	v_add_f32_e32 v147, v147, v171
	v_mul_f32_e32 v147, v211, v147
	v_fmac_f32_e32 v147, s89, v111
	v_mov_b32_e32 v111, v147
	global_store_dwordx4 v77, v[108:111], s[2:3] offset:1024
	global_load_dwordx4 v[140:143], v77, s[4:5] offset:2048
	global_load_dwordx4 v[144:147], v77, s[4:5] offset:3072
	s_add_u32 s4, s4, 0x800000
	s_addc_u32 s5, s5, 0
	global_load_dwordx4 v[148:151], v77, s[4:5] offset:2048
	global_load_dwordx4 v[152:155], v77, s[4:5] offset:3072
	s_add_u32 s4, s4, 0x800000
	s_addc_u32 s5, s5, 0
	global_load_dwordx4 v[156:159], v77, s[4:5] offset:2048
	global_load_dwordx4 v[160:163], v77, s[4:5] offset:3072
	s_add_u32 s4, s4, 0x800000
	s_addc_u32 s5, s5, 0
	global_load_dwordx4 v[164:167], v77, s[4:5] offset:2048
	global_load_dwordx4 v[168:171], v77, s[4:5] offset:3072
	s_sub_u32 s4, s4, 0x1800000
	s_subb_u32 s5, s5, 0
	s_add_u32 s22, s50, 0x3c000
	s_addc_u32 s23, s51, 0
	global_load_dwordx4 v[204:207], v77, s[22:23] offset:2048
	global_load_dwordx4 v[208:211], v77, s[22:23] offset:3072
	s_waitcnt vmcnt(0)
	v_add_f32_e32 v140, v140, v148
	v_add_f32_e32 v140, v140, v156
	v_add_f32_e32 v140, v140, v164
	v_mul_f32_e32 v140, v204, v140
	v_fmac_f32_e32 v140, s89, v112
	v_mov_b32_e32 v112, v140
	v_add_f32_e32 v141, v141, v149
	v_add_f32_e32 v141, v141, v157
	v_add_f32_e32 v141, v141, v165
	v_mul_f32_e32 v141, v205, v141
	v_fmac_f32_e32 v141, s89, v113
	v_mov_b32_e32 v113, v141
	v_add_f32_e32 v142, v142, v150
	v_add_f32_e32 v142, v142, v158
	v_add_f32_e32 v142, v142, v166
	v_mul_f32_e32 v142, v206, v142
	v_fmac_f32_e32 v142, s89, v114
	v_mov_b32_e32 v114, v142
	v_add_f32_e32 v143, v143, v151
	v_add_f32_e32 v143, v143, v159
	v_add_f32_e32 v143, v143, v167
	v_mul_f32_e32 v143, v207, v143
	v_fmac_f32_e32 v143, s89, v115
	v_mov_b32_e32 v115, v143
	global_store_dwordx4 v77, v[112:115], s[2:3] offset:2048
	v_add_f32_e32 v144, v144, v152
	v_add_f32_e32 v144, v144, v160
	v_add_f32_e32 v144, v144, v168
	v_mul_f32_e32 v144, v208, v144
	v_fmac_f32_e32 v144, s89, v116
	v_mov_b32_e32 v116, v144
	v_add_f32_e32 v145, v145, v153
	v_add_f32_e32 v145, v145, v161
	v_add_f32_e32 v145, v145, v169
	v_mul_f32_e32 v145, v209, v145
	v_fmac_f32_e32 v145, s89, v117
	v_mov_b32_e32 v117, v145
	v_add_f32_e32 v146, v146, v154
	v_add_f32_e32 v146, v146, v162
	v_add_f32_e32 v146, v146, v170
	v_mul_f32_e32 v146, v210, v146
	v_fmac_f32_e32 v146, s89, v118
	v_mov_b32_e32 v118, v146
	v_add_f32_e32 v147, v147, v155
	v_add_f32_e32 v147, v147, v163
	v_add_f32_e32 v147, v147, v171
	v_mul_f32_e32 v147, v211, v147
	v_fmac_f32_e32 v147, s89, v119
	v_mov_b32_e32 v119, v147
	global_store_dwordx4 v77, v[116:119], s[2:3] offset:3072
	s_branch .Ll0a_cpart_done
; DI void xcd_barrier(const XcdBarrier& b) {
;     asm volatile("s_waitcnt vmcnt(0)" ::: "memory");
;     __syncthreads();
;     if (threadIdx.x == 0) {
;         unsigned* bar = b.bar;
;         __builtin_amdgcn_s_waitcnt(0);
;         unsigned nloc = b.st[0], nx = b.st[1];
;         if (nloc == 0u) { xcd_barrier_complete(bar, b.x, nloc, nx); b.st[0] = nloc; b.st[1] = nx; }
.Ll0a_done:
	s_waitcnt vmcnt(0)
	s_barrier
	s_and_saveexec_b64 s[6:7], s[24:25]
	s_cbranch_execz .LBB0_1511
	s_add_i32 s2, 0, 0x22000
	v_mov_b32_e32 v0, s2
	s_waitcnt vmcnt(0) expcnt(0) lgkmcnt(0)
	ds_read_b32 v2, v0
	s_add_i32 s2, 0, 0x22004
	v_mov_b32_e32 v0, s2
	ds_read_b32 v0, v0
	s_waitcnt lgkmcnt(1)
	v_cmp_ne_u32_e32 vcc, 0, v2
	s_cbranch_vccnz .LBB0_1475
	s_add_u32 s8, s50, 0x1000
	s_addc_u32 s9, s51, 0
	s_add_u32 s10, s50, 0x1100
	s_addc_u32 s11, s51, 0
	s_add_u32 s12, s50, 0x1200
	s_addc_u32 s13, s51, 0
	s_add_u32 s14, s50, 0x1300
	s_addc_u32 s15, s51, 0
	s_mov_b32 s2, 1
	v_mov_b32_e32 v16, 0
	s_branch .LBB0_1463

; DI int otid() { int t = threadIdx.x; asm volatile("" : "+v"(t)); return t; }
; DI void phase_ln(const Params& p, const float* gam, const float* bet, const float* modnext  , bool skip_ctx, bool final_out,
;                  const float* cgate  , const float* pg, const float* pb  ) {
;     const int tid_ = otid(); const int lane = tid_ & 63, gw = blockIdx.x * 8 + (tid_ >> 6), nw = gridDim.x * 8;
;     float* X = (float*)(p.ws + WS_X); bf16_t* H = (bf16_t*)(p.ws + WS_H); float2* RS = (float2*)(p.ws + WS_RSTAT);
;     for (int rowA = gw; rowA < MR; rowA += 2 * nw) {
;         f32x4 v[2][8]; float sum[2] = {0.f, 0.f}; bool act[2]; int rows[2];
; #pragma unroll
;         for (int q = 0; q < 2; ++q) {
;             const int row = rowA + q * nw; rows[q] = row;
;             const int b = row / RB, r = row % RB;
;             act[q] = row < MR && !(skip_ctx && r < CL);
;             if (act[q]) {
;                 const bool cpart = cgate && r < CL;
;                 float pmu = 0.f, prs = 1.f;
;                 if (cpart && pg) { const float2 st = RS[row]; pmu = st.x; prs = st.y; }
; #pragma unroll
;                 for (int i = 0; i < 8; ++i) {
;                     const int col = (i * 64 + lane) * 4;
;                     v[q][i] = *(const f32x4*)(X + (size_t)row * DM + col);
.LBB0_1840:
	s_or_b64 exec, exec, s[0:1]
	s_waitcnt lgkmcnt(0)
	v_mov_b32_e32 v0, v202
	s_barrier
	v_and_b32_e32 v80, 63, v202
	v_lshrrev_b32_e32 v81, 6, v202
	v_lshlrev_b32_e32 v76, 4, v80
	v_lshlrev_b32_e32 v78, 3, v80
	v_readfirstlane_b32 s35, v81
	v_add_u32_e32 v77, 0x1000, v76
	v_mov_b32_e32 v79, 0
	s_lshl_b32 s9, s26, 3
	s_lshl_b32 s11, s33, 3
	s_nop 0
	s_add_u32 s9, s9, s35
	s_mov_b32 s82, 0x3a000000
	s_mov_b32 s83, 0x3727c5ac
	s_mov_b32 s89, 0x3fb504f3
	s_add_u32 s22, s44, 0x0
	s_addc_u32 s23, s45, 0
	global_load_dwordx4 v[12:15], v76, s[22:23] offset:0
	global_load_dwordx4 v[16:19], v76, s[22:23] offset:1024
	global_load_dwordx4 v[20:23], v76, s[22:23] offset:2048
	global_load_dwordx4 v[24:27], v76, s[22:23] offset:3072
	global_load_dwordx4 v[28:31], v77, s[22:23] offset:0
	global_load_dwordx4 v[32:35], v77, s[22:23] offset:1024
	global_load_dwordx4 v[36:39], v77, s[22:23] offset:2048
	global_load_dwordx4 v[40:43], v77, s[22:23] offset:3072
	s_add_u32 s22, s46, 0x0
	s_addc_u32 s23, s47, 0
	global_load_dwordx4 v[44:47], v76, s[22:23] offset:0
	global_load_dwordx4 v[48:51], v76, s[22:23] offset:1024
	global_load_dwordx4 v[52:55], v76, s[22:23] offset:2048
	global_load_dwordx4 v[56:59], v76, s[22:23] offset:3072
	global_load_dwordx4 v[60:63], v77, s[22:23] offset:0
	global_load_dwordx4 v[64:67], v77, s[22:23] offset:1024
	global_load_dwordx4 v[68:71], v77, s[22:23] offset:2048
	global_load_dwordx4 v[72:75], v77, s[22:23] offset:3072

; DI void phase_ln(const Params& p, const float* gam, const float* bet, const float* modnext  , bool skip_ctx, bool final_out,
;                  const float* cgate  , const float* pg, const float* pb  ) {
;     ...
; #pragma unroll
;         for (int q = 0; q < 2; ++q)
; #pragma unroll
;             for (int i = 0; i < 8; ++i) sum[q] += v[q][i][0] + v[q][i][1] + v[q][i][2] + v[q][i][3];
;         float mu[2], sq[2] = {0.f, 0.f}, rs[2];
; #pragma unroll
;         for (int o = 32; o > 0; o >>= 1) { sum[0] += __shfl_xor(sum[0], o); sum[1] += __shfl_xor(sum[1], o); }
; #pragma unroll
;         for (int q = 0; q < 2; ++q) {
;             mu[q] = sum[q] * (1.f / 2048.f);
; #pragma unroll
;             for (int i = 0; i < 8; ++i) { v[q][i] -= mu[q]; sq[q] += v[q][i][0] * v[q][i][0] + v[q][i][1] * v[q][i][1] + v[q][i][2] * v[q][i][2] + v[q][i][3] * v[q][i][3]; }
;         }
; #pragma unroll
;         for (int o = 32; o > 0; o >>= 1) { sq[0] += __shfl_xor(sq[0], o); sq[1] += __shfl_xor(sq[1], o); }
; #pragma unroll
;         for (int q = 0; q < 2; ++q) {
;             if (!act[q]) continue;
;             rs[q] = rsqrtf(sq[q] * (1.f / 2048.f) + 1e-5f);
;             const int row = rows[q]; const int b = row / RB, r = row % RB; const int s = r < CL ? 4 : b;
;             if (lane == 0 && !final_out) RS[row] = make_float2(mu[q], rs[q]);
.Ll0b_cpart_done:
	s_mul_i32 s35, s32, 0xc000
	s_add_u32 s4, s50, 0x44000
	s_addc_u32 s5, s51, 0
	s_add_u32 s4, s4, s35
	s_addc_u32 s5, s5, 0
	global_load_dwordx4 v[140:143], v76, s[4:5] offset:0
	global_load_dwordx4 v[144:147], v76, s[4:5] offset:1024
	global_load_dwordx4 v[148:151], v76, s[4:5] offset:2048
	global_load_dwordx4 v[152:155], v76, s[4:5] offset:3072
	global_load_dwordx4 v[156:159], v77, s[4:5] offset:0
	global_load_dwordx4 v[160:163], v77, s[4:5] offset:1024
	global_load_dwordx4 v[164:167], v77, s[4:5] offset:2048
	global_load_dwordx4 v[168:171], v77, s[4:5] offset:3072
	s_add_u32 s4, s4, 0x2000
	s_addc_u32 s5, s5, 0
	global_load_dwordx4 v[204:207], v76, s[4:5] offset:0
	global_load_dwordx4 v[208:211], v76, s[4:5] offset:1024
	global_load_dwordx4 v[212:215], v76, s[4:5] offset:2048
	global_load_dwordx4 v[216:219], v76, s[4:5] offset:3072
	global_load_dwordx4 v[220:223], v77, s[4:5] offset:0
	global_load_dwordx4 v[224:227], v77, s[4:5] offset:1024
	global_load_dwordx4 v[228:231], v77, s[4:5] offset:2048
	global_load_dwordx4 v[232:235], v77, s[4:5] offset:3072
	s_waitcnt vmcnt(16)
	v_add_f32_e32 v80, v88, v92
	v_add_f32_e32 v81, v89, v93
	v_add_f32_e32 v82, v90, v94
	v_add_f32_e32 v83, v91, v95
	v_add_f32_e32 v80, v96, v80
	v_add_f32_e32 v81, v97, v81
	v_add_f32_e32 v82, v98, v82
	v_add_f32_e32 v83, v99, v83
	v_add_f32_e32 v80, v100, v80
	v_add_f32_e32 v81, v101, v81
	v_add_f32_e32 v82, v102, v82
	v_add_f32_e32 v83, v103, v83
	v_add_f32_e32 v80, v104, v80
	v_add_f32_e32 v81, v105, v81
	v_add_f32_e32 v82, v106, v82
	v_add_f32_e32 v83, v107, v83
	v_add_f32_e32 v80, v108, v80
	v_add_f32_e32 v81, v109, v81
	v_add_f32_e32 v82, v110, v82
	v_add_f32_e32 v83, v111, v83
	v_add_f32_e32 v80, v112, v80
	v_add_f32_e32 v81, v113, v81
	v_add_f32_e32 v82, v114, v82
	v_add_f32_e32 v83, v115, v83
	v_add_f32_e32 v80, v116, v80
	v_add_f32_e32 v81, v117, v81
	v_add_f32_e32 v82, v118, v82
	v_add_f32_e32 v83, v119, v83
	v_add_f32_e32 v80, v80, v81
	v_add_f32_e32 v82, v82, v83
	v_add_f32_e32 v80, v80, v82
	s_nop 1
	v_add_f32_dpp v86, v80, v80 quad_perm:[1,0,3,2] row_mask:0xf bank_mask:0xf
	s_nop 1
	v_add_f32_dpp v86, v86, v86 quad_perm:[2,3,0,1] row_mask:0xf bank_mask:0xf
	s_nop 1
	v_add_f32_dpp v86, v86, v86 row_half_mirror row_mask:0xf bank_mask:0xf
	s_nop 1
	v_add_f32_dpp v86, v86, v86 row_mirror row_mask:0xf bank_mask:0xf
	s_nop 1
	v_readlane_b32 s69, v86, 0
	v_readlane_b32 s71, v86, 16
	v_readlane_b32 s73, v86, 32
	v_readlane_b32 s81, v86, 48
	s_nop 3
	v_mov_b32_e32 v84, s69
	v_add_f32_e32 v84, s71, v84
	v_add_f32_e32 v84, s73, v84
	v_add_f32_e32 v84, s81, v84
	v_mul_f32_e32 v236, s82, v84
	v_sub_f32_e32 v88, v88, v236
	v_sub_f32_e32 v89, v89, v236
	v_sub_f32_e32 v90, v90, v236
	v_sub_f32_e32 v91, v91, v236
	v_sub_f32_e32 v92, v92, v236
	v_sub_f32_e32 v93, v93, v236
	v_sub_f32_e32 v94, v94, v236
	v_sub_f32_e32 v95, v95, v236
	v_sub_f32_e32 v96, v96, v236
	v_sub_f32_e32 v97, v97, v236
	v_sub_f32_e32 v98, v98, v236
	v_sub_f32_e32 v99, v99, v236
	v_sub_f32_e32 v100, v100, v236
	v_sub_f32_e32 v101, v101, v236
	v_sub_f32_e32 v102, v102, v236
	v_sub_f32_e32 v103, v103, v236
	v_sub_f32_e32 v104, v104, v236
	v_sub_f32_e32 v105, v105, v236
	v_sub_f32_e32 v106, v106, v236
	v_sub_f32_e32 v107, v107, v236
	v_sub_f32_e32 v108, v108, v236
	v_sub_f32_e32 v109, v109, v236
	v_sub_f32_e32 v110, v110, v236
	v_sub_f32_e32 v111, v111, v236
	v_sub_f32_e32 v112, v112, v236
	v_sub_f32_e32 v113, v113, v236
	v_sub_f32_e32 v114, v114, v236
	v_sub_f32_e32 v115, v115, v236
	v_sub_f32_e32 v116, v116, v236
	v_sub_f32_e32 v117, v117, v236
	v_sub_f32_e32 v118, v118, v236
	v_sub_f32_e32 v119, v119, v236
	v_mul_f32_e32 v80, v88, v88
	v_mul_f32_e32 v81, v89, v89
	v_mul_f32_e32 v82, v90, v90
	v_mul_f32_e32 v83, v91, v91
	v_fmac_f32_e32 v80, v92, v92
	v_fmac_f32_e32 v81, v93, v93
	v_fmac_f32_e32 v82, v94, v94
	v_fmac_f32_e32 v83, v95, v95
	v_fmac_f32_e32 v80, v96, v96
	v_fmac_f32_e32 v81, v97, v97
	v_fmac_f32_e32 v82, v98, v98
	v_fmac_f32_e32 v83, v99, v99
	v_fmac_f32_e32 v80, v100, v100
	v_fmac_f32_e32 v81, v101, v101
	v_fmac_f32_e32 v82, v102, v102
	v_fmac_f32_e32 v83, v103, v103
	v_fmac_f32_e32 v80, v104, v104
	v_fmac_f32_e32 v81, v105, v105
	v_fmac_f32_e32 v82, v106, v106
	v_fmac_f32_e32 v83, v107, v107
	v_fmac_f32_e32 v80, v108, v108
	v_fmac_f32_e32 v81, v109, v109
	v_fmac_f32_e32 v82, v110, v110
	v_fmac_f32_e32 v83, v111, v111
	v_fmac_f32_e32 v80, v112, v112
	v_fmac_f32_e32 v81, v113, v113
	v_fmac_f32_e32 v82, v114, v114
	v_fmac_f32_e32 v83, v115, v115
	v_fmac_f32_e32 v80, v116, v116
	v_fmac_f32_e32 v81, v117, v117
	v_fmac_f32_e32 v82, v118, v118
	v_fmac_f32_e32 v83, v119, v119
	v_add_f32_e32 v80, v80, v81
	v_add_f32_e32 v82, v82, v83
	v_add_f32_e32 v80, v80, v82
	s_nop 1
	v_add_f32_dpp v86, v80, v80 quad_perm:[1,0,3,2] row_mask:0xf bank_mask:0xf
	s_nop 1
	v_add_f32_dpp v86, v86, v86 quad_perm:[2,3,0,1] row_mask:0xf bank_mask:0xf
	s_nop 1
	v_add_f32_dpp v86, v86, v86 row_half_mirror row_mask:0xf bank_mask:0xf
	s_nop 1
	v_add_f32_dpp v86, v86, v86 row_mirror row_mask:0xf bank_mask:0xf
	s_nop 1
	v_readlane_b32 s69, v86, 0
	v_readlane_b32 s71, v86, 16
	v_readlane_b32 s73, v86, 32
	v_readlane_b32 s81, v86, 48
	s_nop 3
	v_mov_b32_e32 v84, s69
	v_add_f32_e32 v84, s71, v84
	v_add_f32_e32 v84, s73, v84
	v_add_f32_e32 v84, s81, v84
	v_mov_b32_e32 v86, s83
	v_fmac_f32_e32 v86, s82, v84
	v_rsq_f32_e32 v237, v86
	s_nop 0
	s_lshl_b32 s35, s9, 3
	s_add_u32 s22, s50, 0x260a0000
	s_addc_u32 s23, s51, 0
	s_add_u32 s22, s22, s35
	s_addc_u32 s23, s23, 0
	s_mov_b64 s[74:75], exec
	s_mov_b64 exec, 1
	global_store_dwordx2 v79, v[236:237], s[22:23]
	s_mov_b64 exec, s[74:75]
	s_lshl_b32 s35, s9, 12
	s_add_u32 s6, s50, 0x23ca0000
	s_addc_u32 s7, s51, 0
	s_add_u32 s6, s6, s35
	s_addc_u32 s7, s7, 0
	s_waitcnt vmcnt(1)
; DI void st_bf16x4(bf16_t* p, f32x4 v) { u32x2 w; w.x = cvt_pk_bf16(v[0], v[1]); w.y = cvt_pk_bf16(v[2], v[3]); *(u32x2*)p = w; }
; DI void phase_ln(const Params& p, const float* gam, const float* bet, const float* modnext  , bool skip_ctx, bool final_out,
;                  const float* cgate  , const float* pg, const float* pb  ) {
;     ...
; #pragma unroll
;             for (int i = 0; i < 8; ++i) {
;                 const int col = (i * 64 + lane) * 4;
;                 const f32x4 o = v[q][i] * rs[q] * *(const f32x4*)(gam + col) + *(const f32x4*)(bet + col);
;                 if (final_out) { *(f32x4*)(p.out + ((size_t)b * TL + (r - CL)) * DM + col) = o; }
;                 else {
;                     const f32x4 s4 = *(const f32x4*)(modnext + (size_t)s * 12288 + col), c4 = *(const f32x4*)(modnext + (size_t)s * 12288 + 2048 + col);
;                     st_bf16x4(H + (size_t)row * DM + col, o * (c4 + 1.f) + s4);
;                 }
	v_mul_f32_e32 v88, v88, v237
	v_mul_f32_e32 v89, v89, v237
	v_mul_f32_e32 v90, v90, v237
	v_mul_f32_e32 v91, v91, v237
	v_fma_f32 v88, v88, v12, v44
	v_fma_f32 v89, v89, v13, v45
	v_fma_f32 v90, v90, v14, v46
	v_fma_f32 v91, v91, v15, v47
	v_add_f32_e32 v204, 1.0, v204
	v_add_f32_e32 v205, 1.0, v205
	v_add_f32_e32 v206, 1.0, v206
	v_add_f32_e32 v207, 1.0, v207
	v_fma_f32 v88, v88, v204, v140
	v_fma_f32 v89, v89, v205, v141
	v_fma_f32 v90, v90, v206, v142
	v_fma_f32 v91, v91, v207, v143
	v_cvt_pk_bf16_f32 v88, v88, v89
	v_cvt_pk_bf16_f32 v89, v90, v91
	global_store_dwordx2 v78, v[88:89], s[6:7] offset:0
	v_mul_f32_e32 v92, v92, v237
	v_mul_f32_e32 v93, v93, v237
	v_mul_f32_e32 v94, v94, v237
	v_mul_f32_e32 v95, v95, v237
	v_fma_f32 v92, v92, v16, v48
	v_fma_f32 v93, v93, v17, v49
	v_fma_f32 v94, v94, v18, v50
	v_fma_f32 v95, v95, v19, v51
	v_add_f32_e32 v208, 1.0, v208
	v_add_f32_e32 v209, 1.0, v209
	v_add_f32_e32 v210, 1.0, v210
	v_add_f32_e32 v211, 1.0, v211
	v_fma_f32 v92, v92, v208, v144
	v_fma_f32 v93, v93, v209, v145
	v_fma_f32 v94, v94, v210, v146
	v_fma_f32 v95, v95, v211, v147
	v_cvt_pk_bf16_f32 v92, v92, v93
	v_cvt_pk_bf16_f32 v93, v94, v95
	global_store_dwordx2 v78, v[92:93], s[6:7] offset:512
	v_mul_f32_e32 v96, v96, v237
	v_mul_f32_e32 v97, v97, v237
	v_mul_f32_e32 v98, v98, v237
	v_mul_f32_e32 v99, v99, v237
	v_fma_f32 v96, v96, v20, v52
	v_fma_f32 v97, v97, v21, v53
	v_fma_f32 v98, v98, v22, v54
	v_fma_f32 v99, v99, v23, v55
	v_add_f32_e32 v212, 1.0, v212
	v_add_f32_e32 v213, 1.0, v213
	v_add_f32_e32 v214, 1.0, v214
	v_add_f32_e32 v215, 1.0, v215
	v_fma_f32 v96, v96, v212, v148
	v_fma_f32 v97, v97, v213, v149
	v_fma_f32 v98, v98, v214, v150
	v_fma_f32 v99, v99, v215, v151
	v_cvt_pk_bf16_f32 v96, v96, v97
	v_cvt_pk_bf16_f32 v97, v98, v99
	global_store_dwordx2 v78, v[96:97], s[6:7] offset:1024
	v_mul_f32_e32 v100, v100, v237
	v_mul_f32_e32 v101, v101, v237
	v_mul_f32_e32 v102, v102, v237
	v_mul_f32_e32 v103, v103, v237
	v_fma_f32 v100, v100, v24, v56
	v_fma_f32 v101, v101, v25, v57
	v_fma_f32 v102, v102, v26, v58
	v_fma_f32 v103, v103, v27, v59
	v_add_f32_e32 v216, 1.0, v216
	v_add_f32_e32 v217, 1.0, v217
	v_add_f32_e32 v218, 1.0, v218
	v_add_f32_e32 v219, 1.0, v219
	v_fma_f32 v100, v100, v216, v152
	v_fma_f32 v101, v101, v217, v153
	v_fma_f32 v102, v102, v218, v154
	v_fma_f32 v103, v103, v219, v155
	v_cvt_pk_bf16_f32 v100, v100, v101
	v_cvt_pk_bf16_f32 v101, v102, v103
	global_store_dwordx2 v78, v[100:101], s[6:7] offset:1536
	v_mul_f32_e32 v104, v104, v237
	v_mul_f32_e32 v105, v105, v237
	v_mul_f32_e32 v106, v106, v237
	v_mul_f32_e32 v107, v107, v237
	v_fma_f32 v104, v104, v28, v60
	v_fma_f32 v105, v105, v29, v61
	v_fma_f32 v106, v106, v30, v62
	v_fma_f32 v107, v107, v31, v63
	v_add_f32_e32 v220, 1.0, v220
	v_add_f32_e32 v221, 1.0, v221
	v_add_f32_e32 v222, 1.0, v222
	v_add_f32_e32 v223, 1.0, v223
	v_fma_f32 v104, v104, v220, v156
	v_fma_f32 v105, v105, v221, v157
	v_fma_f32 v106, v106, v222, v158
	v_fma_f32 v107, v107, v223, v159
	v_cvt_pk_bf16_f32 v104, v104, v105
	v_cvt_pk_bf16_f32 v105, v106, v107
	global_store_dwordx2 v78, v[104:105], s[6:7] offset:2048
	v_mul_f32_e32 v108, v108, v237
	v_mul_f32_e32 v109, v109, v237
	v_mul_f32_e32 v110, v110, v237
	v_mul_f32_e32 v111, v111, v237
	v_fma_f32 v108, v108, v32, v64
	v_fma_f32 v109, v109, v33, v65
	v_fma_f32 v110, v110, v34, v66
	v_fma_f32 v111, v111, v35, v67
	v_add_f32_e32 v224, 1.0, v224
	v_add_f32_e32 v225, 1.0, v225
	v_add_f32_e32 v226, 1.0, v226
	v_add_f32_e32 v227, 1.0, v227
	v_fma_f32 v108, v108, v224, v160
	v_fma_f32 v109, v109, v225, v161
	v_fma_f32 v110, v110, v226, v162
	v_fma_f32 v111, v111, v227, v163
	v_cvt_pk_bf16_f32 v108, v108, v109
	v_cvt_pk_bf16_f32 v109, v110, v111
	global_store_dwordx2 v78, v[108:109], s[6:7] offset:2560
	v_mul_f32_e32 v112, v112, v237
	v_mul_f32_e32 v113, v113, v237
	v_mul_f32_e32 v114, v114, v237
	v_mul_f32_e32 v115, v115, v237
	v_fma_f32 v112, v112, v36, v68
	v_fma_f32 v113, v113, v37, v69
	v_fma_f32 v114, v114, v38, v70
	v_fma_f32 v115, v115, v39, v71
	v_add_f32_e32 v228, 1.0, v228
	v_add_f32_e32 v229, 1.0, v229
	v_add_f32_e32 v230, 1.0, v230
	v_add_f32_e32 v231, 1.0, v231
	v_fma_f32 v112, v112, v228, v164
	v_fma_f32 v113, v113, v229, v165
	v_fma_f32 v114, v114, v230, v166
	v_fma_f32 v115, v115, v231, v167
	v_cvt_pk_bf16_f32 v112, v112, v113
	v_cvt_pk_bf16_f32 v113, v114, v115
	global_store_dwordx2 v78, v[112:113], s[6:7] offset:3072
	v_mul_f32_e32 v116, v116, v237
	v_mul_f32_e32 v117, v117, v237
	v_mul_f32_e32 v118, v118, v237
	v_mul_f32_e32 v119, v119, v237
	v_fma_f32 v116, v116, v40, v72
	v_fma_f32 v117, v117, v41, v73
	v_fma_f32 v118, v118, v42, v74
	v_fma_f32 v119, v119, v43, v75
	v_add_f32_e32 v232, 1.0, v232
	v_add_f32_e32 v233, 1.0, v233
	v_add_f32_e32 v234, 1.0, v234
	v_add_f32_e32 v235, 1.0, v235
	v_fma_f32 v116, v116, v232, v168
	v_fma_f32 v117, v117, v233, v169
	v_fma_f32 v118, v118, v234, v170
	v_fma_f32 v119, v119, v235, v171
	v_cvt_pk_bf16_f32 v116, v116, v117
	v_cvt_pk_bf16_f32 v117, v118, v119
	global_store_dwordx2 v78, v[116:117], s[6:7] offset:3584

; DI void phase_ln(const Params& p, const float* gam, const float* bet, const float* modnext  , bool skip_ctx, bool final_out,
;                  const float* cgate  , const float* pg, const float* pb  ) {
;     ...
;                 const bool cpart = cgate && r < CL;
;                 float pmu = 0.f, prs = 1.f;
;                 if (cpart && pg) { const float2 st = RS[row]; pmu = st.x; prs = st.y; }
; #pragma unroll
;                 for (int i = 0; i < 8; ++i) {
;                     const int col = (i * 64 + lane) * 4;
;                     v[q][i] = *(const f32x4*)(X + (size_t)row * DM + col);
;                     if (cpart) {
;                         if (pg) v[q][i] = (v[q][i] - pmu) * prs * *(const f32x4*)(pg + col) + *(const f32x4*)(pb + col);
;                         const float* pt = (const float*)(p.ws + WS_PART) + ((size_t)b * 256 + r) * DM + col;
;                         const f32x4 ps = *(const f32x4*)pt + *(const f32x4*)(pt + (size_t)1024 * DM) + *(const f32x4*)(pt + (size_t)2048 * DM) + *(const f32x4*)(pt + (size_t)3072 * DM);
;                         v[q][i] = v[q][i] * ALPHA + *(const f32x4*)(cgate + col) * ps;
;                         *(f32x4*)(X + (size_t)row * DM + col) = v[q][i];
.Ll0b_cpart:
	s_lshl_b32 s35, s27, 8
	s_add_u32 s35, s35, s29
	s_lshl_b32 s35, s35, 13
	s_add_u32 s4, s50, 0x123a0000
	s_addc_u32 s5, s51, 0
	s_add_u32 s4, s4, s35
	s_addc_u32 s5, s5, 0
	s_lshl_b32 s35, s9, 3
	s_add_u32 s22, s50, 0x260a0000
	s_addc_u32 s23, s51, 0
	s_add_u32 s22, s22, s35
	s_addc_u32 s23, s23, 0
	global_load_dwordx2 v[238:239], v79, s[22:23]
	global_load_dwordx4 v[140:143], v76, s[4:5] offset:0
	global_load_dwordx4 v[144:147], v76, s[4:5] offset:1024
	s_add_u32 s4, s4, 0x800000
	s_addc_u32 s5, s5, 0
	global_load_dwordx4 v[148:151], v76, s[4:5] offset:0
	global_load_dwordx4 v[152:155], v76, s[4:5] offset:1024
	s_add_u32 s4, s4, 0x800000
	s_addc_u32 s5, s5, 0
	global_load_dwordx4 v[156:159], v76, s[4:5] offset:0
	global_load_dwordx4 v[160:163], v76, s[4:5] offset:1024
	s_add_u32 s4, s4, 0x800000
	s_addc_u32 s5, s5, 0
	global_load_dwordx4 v[164:167], v76, s[4:5] offset:0
	global_load_dwordx4 v[168:171], v76, s[4:5] offset:1024
	s_sub_u32 s4, s4, 0x1800000
	s_subb_u32 s5, s5, 0
	s_add_u32 s22, s50, 0x42000
	s_addc_u32 s23, s51, 0
	global_load_dwordx4 v[204:207], v76, s[22:23] offset:0
	global_load_dwordx4 v[208:211], v76, s[22:23] offset:1024
	global_load_dwordx4 v[212:215], v76, s[64:65] offset:0
	global_load_dwordx4 v[216:219], v76, s[64:65] offset:1024
	global_load_dwordx4 v[220:223], v76, s[66:67] offset:0
	global_load_dwordx4 v[224:227], v76, s[66:67] offset:1024
	s_waitcnt vmcnt(0)
	v_sub_f32_e32 v88, v88, v238
	v_mul_f32_e32 v88, v88, v239
	v_fma_f32 v88, v88, v212, v220
	v_add_f32_e32 v140, v140, v148
	v_add_f32_e32 v140, v140, v156
	v_add_f32_e32 v140, v140, v164
	v_mul_f32_e32 v140, v204, v140
	v_fmac_f32_e32 v140, s89, v88
	v_mov_b32_e32 v88, v140
	v_sub_f32_e32 v89, v89, v238
	v_mul_f32_e32 v89, v89, v239
	v_fma_f32 v89, v89, v213, v221
	v_add_f32_e32 v141, v141, v149
	v_add_f32_e32 v141, v141, v157
	v_add_f32_e32 v141, v141, v165
	v_mul_f32_e32 v141, v205, v141
	v_fmac_f32_e32 v141, s89, v89
	v_mov_b32_e32 v89, v141
	v_sub_f32_e32 v90, v90, v238
	v_mul_f32_e32 v90, v90, v239
	v_fma_f32 v90, v90, v214, v222
	v_add_f32_e32 v142, v142, v150
	v_add_f32_e32 v142, v142, v158
	v_add_f32_e32 v142, v142, v166
	v_mul_f32_e32 v142, v206, v142
	v_fmac_f32_e32 v142, s89, v90
	v_mov_b32_e32 v90, v142
	v_sub_f32_e32 v91, v91, v238
	v_mul_f32_e32 v91, v91, v239
	v_fma_f32 v91, v91, v215, v223
	v_add_f32_e32 v143, v143, v151
	v_add_f32_e32 v143, v143, v159
	v_add_f32_e32 v143, v143, v167
	v_mul_f32_e32 v143, v207, v143
	v_fmac_f32_e32 v143, s89, v91
	v_mov_b32_e32 v91, v143
	global_store_dwordx4 v76, v[88:91], s[2:3] offset:0
	v_sub_f32_e32 v92, v92, v238
	v_mul_f32_e32 v92, v92, v239
	v_fma_f32 v92, v92, v216, v224
	v_add_f32_e32 v144, v144, v152
	v_add_f32_e32 v144, v144, v160
	v_add_f32_e32 v144, v144, v168
	v_mul_f32_e32 v144, v208, v144
	v_fmac_f32_e32 v144, s89, v92
	v_mov_b32_e32 v92, v144
	v_sub_f32_e32 v93, v93, v238
	v_mul_f32_e32 v93, v93, v239
	v_fma_f32 v93, v93, v217, v225
	v_add_f32_e32 v145, v145, v153
	v_add_f32_e32 v145, v145, v161
	v_add_f32_e32 v145, v145, v169
	v_mul_f32_e32 v145, v209, v145
	v_fmac_f32_e32 v145, s89, v93
	v_mov_b32_e32 v93, v145
	v_sub_f32_e32 v94, v94, v238
	v_mul_f32_e32 v94, v94, v239
	v_fma_f32 v94, v94, v218, v226
	v_add_f32_e32 v146, v146, v154
	v_add_f32_e32 v146, v146, v162
	v_add_f32_e32 v146, v146, v170
	v_mul_f32_e32 v146, v210, v146
	v_fmac_f32_e32 v146, s89, v94
	v_mov_b32_e32 v94, v146
	v_sub_f32_e32 v95, v95, v238
	v_mul_f32_e32 v95, v95, v239
	v_fma_f32 v95, v95, v219, v227
	v_add_f32_e32 v147, v147, v155
	v_add_f32_e32 v147, v147, v163
	v_add_f32_e32 v147, v147, v171
	v_mul_f32_e32 v147, v211, v147
	v_fmac_f32_e32 v147, s89, v95
	v_mov_b32_e32 v95, v147
	global_store_dwordx4 v76, v[92:95], s[2:3] offset:1024
	global_load_dwordx4 v[140:143], v76, s[4:5] offset:2048
	global_load_dwordx4 v[144:147], v76, s[4:5] offset:3072
	s_add_u32 s4, s4, 0x800000
	s_addc_u32 s5, s5, 0
	global_load_dwordx4 v[148:151], v76, s[4:5] offset:2048
	global_load_dwordx4 v[152:155], v76, s[4:5] offset:3072
	s_add_u32 s4, s4, 0x800000
	s_addc_u32 s5, s5, 0
	global_load_dwordx4 v[156:159], v76, s[4:5] offset:2048
	global_load_dwordx4 v[160:163], v76, s[4:5] offset:3072
	s_add_u32 s4, s4, 0x800000
	s_addc_u32 s5, s5, 0
	global_load_dwordx4 v[164:167], v76, s[4:5] offset:2048
	global_load_dwordx4 v[168:171], v76, s[4:5] offset:3072
	s_sub_u32 s4, s4, 0x1800000
	s_subb_u32 s5, s5, 0
	s_add_u32 s22, s50, 0x42000
	s_addc_u32 s23, s51, 0
	global_load_dwordx4 v[204:207], v76, s[22:23] offset:2048
	global_load_dwordx4 v[208:211], v76, s[22:23] offset:3072
	global_load_dwordx4 v[212:215], v76, s[64:65] offset:2048
	global_load_dwordx4 v[216:219], v76, s[64:65] offset:3072
	global_load_dwordx4 v[220:223], v76, s[66:67] offset:2048
	global_load_dwordx4 v[224:227], v76, s[66:67] offset:3072
	s_waitcnt vmcnt(0)
; DI void phase_ln(const Params& p, const float* gam, const float* bet, const float* modnext  , bool skip_ctx, bool final_out,
;                  const float* cgate  , const float* pg, const float* pb  ) {
;     ...
;                 const bool cpart = cgate && r < CL;
;                 float pmu = 0.f, prs = 1.f;
;                 if (cpart && pg) { const float2 st = RS[row]; pmu = st.x; prs = st.y; }
; #pragma unroll
;                 for (int i = 0; i < 8; ++i) {
;                     const int col = (i * 64 + lane) * 4;
;                     v[q][i] = *(const f32x4*)(X + (size_t)row * DM + col);
;                     if (cpart) {
;                         if (pg) v[q][i] = (v[q][i] - pmu) * prs * *(const f32x4*)(pg + col) + *(const f32x4*)(pb + col);
;                         const float* pt = (const float*)(p.ws + WS_PART) + ((size_t)b * 256 + r) * DM + col;
;                         const f32x4 ps = *(const f32x4*)pt + *(const f32x4*)(pt + (size_t)1024 * DM) + *(const f32x4*)(pt + (size_t)2048 * DM) + *(const f32x4*)(pt + (size_t)3072 * DM);
;                         v[q][i] = v[q][i] * ALPHA + *(const f32x4*)(cgate + col) * ps;
;                         *(f32x4*)(X + (size_t)row * DM + col) = v[q][i];
	v_sub_f32_e32 v96, v96, v238
	v_mul_f32_e32 v96, v96, v239
	v_fma_f32 v96, v96, v212, v220
	v_add_f32_e32 v140, v140, v148
	v_add_f32_e32 v140, v140, v156
	v_add_f32_e32 v140, v140, v164
	v_mul_f32_e32 v140, v204, v140
	v_fmac_f32_e32 v140, s89, v96
	v_mov_b32_e32 v96, v140
	v_sub_f32_e32 v97, v97, v238
	v_mul_f32_e32 v97, v97, v239
	v_fma_f32 v97, v97, v213, v221
	v_add_f32_e32 v141, v141, v149
	v_add_f32_e32 v141, v141, v157
	v_add_f32_e32 v141, v141, v165
	v_mul_f32_e32 v141, v205, v141
	v_fmac_f32_e32 v141, s89, v97
	v_mov_b32_e32 v97, v141
	v_sub_f32_e32 v98, v98, v238
	v_mul_f32_e32 v98, v98, v239
	v_fma_f32 v98, v98, v214, v222
	v_add_f32_e32 v142, v142, v150
	v_add_f32_e32 v142, v142, v158
	v_add_f32_e32 v142, v142, v166
	v_mul_f32_e32 v142, v206, v142
	v_fmac_f32_e32 v142, s89, v98
	v_mov_b32_e32 v98, v142
	v_sub_f32_e32 v99, v99, v238
	v_mul_f32_e32 v99, v99, v239
	v_fma_f32 v99, v99, v215, v223
	v_add_f32_e32 v143, v143, v151
	v_add_f32_e32 v143, v143, v159
	v_add_f32_e32 v143, v143, v167
	v_mul_f32_e32 v143, v207, v143
	v_fmac_f32_e32 v143, s89, v99
	v_mov_b32_e32 v99, v143
	global_store_dwordx4 v76, v[96:99], s[2:3] offset:2048
	v_sub_f32_e32 v100, v100, v238
	v_mul_f32_e32 v100, v100, v239
	v_fma_f32 v100, v100, v216, v224
	v_add_f32_e32 v144, v144, v152
	v_add_f32_e32 v144, v144, v160
	v_add_f32_e32 v144, v144, v168
	v_mul_f32_e32 v144, v208, v144
	v_fmac_f32_e32 v144, s89, v100
	v_mov_b32_e32 v100, v144
	v_sub_f32_e32 v101, v101, v238
	v_mul_f32_e32 v101, v101, v239
	v_fma_f32 v101, v101, v217, v225
	v_add_f32_e32 v145, v145, v153
	v_add_f32_e32 v145, v145, v161
	v_add_f32_e32 v145, v145, v169
	v_mul_f32_e32 v145, v209, v145
	v_fmac_f32_e32 v145, s89, v101
	v_mov_b32_e32 v101, v145
	v_sub_f32_e32 v102, v102, v238
	v_mul_f32_e32 v102, v102, v239
	v_fma_f32 v102, v102, v218, v226
	v_add_f32_e32 v146, v146, v154
	v_add_f32_e32 v146, v146, v162
	v_add_f32_e32 v146, v146, v170
	v_mul_f32_e32 v146, v210, v146
	v_fmac_f32_e32 v146, s89, v102
	v_mov_b32_e32 v102, v146
	v_sub_f32_e32 v103, v103, v238
	v_mul_f32_e32 v103, v103, v239
	v_fma_f32 v103, v103, v219, v227
	v_add_f32_e32 v147, v147, v155
	v_add_f32_e32 v147, v147, v163
	v_add_f32_e32 v147, v147, v171
	v_mul_f32_e32 v147, v211, v147
	v_fmac_f32_e32 v147, s89, v103
	v_mov_b32_e32 v103, v147
	global_store_dwordx4 v76, v[100:103], s[2:3] offset:3072
	global_load_dwordx4 v[140:143], v77, s[4:5] offset:0
	global_load_dwordx4 v[144:147], v77, s[4:5] offset:1024
	s_add_u32 s4, s4, 0x800000
	s_addc_u32 s5, s5, 0
	global_load_dwordx4 v[148:151], v77, s[4:5] offset:0
	global_load_dwordx4 v[152:155], v77, s[4:5] offset:1024
	s_add_u32 s4, s4, 0x800000
	s_addc_u32 s5, s5, 0
	global_load_dwordx4 v[156:159], v77, s[4:5] offset:0
	global_load_dwordx4 v[160:163], v77, s[4:5] offset:1024
	s_add_u32 s4, s4, 0x800000
	s_addc_u32 s5, s5, 0
	global_load_dwordx4 v[164:167], v77, s[4:5] offset:0
	global_load_dwordx4 v[168:171], v77, s[4:5] offset:1024
	s_sub_u32 s4, s4, 0x1800000
	s_subb_u32 s5, s5, 0
	s_add_u32 s22, s50, 0x42000
	s_addc_u32 s23, s51, 0
	global_load_dwordx4 v[204:207], v77, s[22:23] offset:0
	global_load_dwordx4 v[208:211], v77, s[22:23] offset:1024
	global_load_dwordx4 v[212:215], v77, s[64:65] offset:0
	global_load_dwordx4 v[216:219], v77, s[64:65] offset:1024
	global_load_dwordx4 v[220:223], v77, s[66:67] offset:0
	global_load_dwordx4 v[224:227], v77, s[66:67] offset:1024
	s_waitcnt vmcnt(0)
; DI void xcd_barrier(const XcdBarrier& b) {
;     asm volatile("s_waitcnt vmcnt(0)" ::: "memory");
;     __syncthreads();
;     if (threadIdx.x == 0) {
;         unsigned* bar = b.bar;
;         __builtin_amdgcn_s_waitcnt(0);
;         unsigned nloc = b.st[0], nx = b.st[1];
;         if (nloc == 0u) { xcd_barrier_complete(bar, b.x, nloc, nx); b.st[0] = nloc; b.st[1] = nx; }
; DI void phase_ln(const Params& p, const float* gam, const float* bet, const float* modnext  , bool skip_ctx, bool final_out,
;                  const float* cgate  , const float* pg, const float* pb  ) {
;     ...
;                 const bool cpart = cgate && r < CL;
;                 float pmu = 0.f, prs = 1.f;
;                 if (cpart && pg) { const float2 st = RS[row]; pmu = st.x; prs = st.y; }
; #pragma unroll
;                 for (int i = 0; i < 8; ++i) {
;                     const int col = (i * 64 + lane) * 4;
;                     v[q][i] = *(const f32x4*)(X + (size_t)row * DM + col);
;                     if (cpart) {
;                         if (pg) v[q][i] = (v[q][i] - pmu) * prs * *(const f32x4*)(pg + col) + *(const f32x4*)(pb + col);
;                         const float* pt = (const float*)(p.ws + WS_PART) + ((size_t)b * 256 + r) * DM + col;
;                         const f32x4 ps = *(const f32x4*)pt + *(const f32x4*)(pt + (size_t)1024 * DM) + *(const f32x4*)(pt + (size_t)2048 * DM) + *(const f32x4*)(pt + (size_t)3072 * DM);
;                         v[q][i] = v[q][i] * ALPHA + *(const f32x4*)(cgate + col) * ps;
;                         *(f32x4*)(X + (size_t)row * DM + col) = v[q][i];
	v_sub_f32_e32 v104, v104, v238
	v_mul_f32_e32 v104, v104, v239
	v_fma_f32 v104, v104, v212, v220
	v_add_f32_e32 v140, v140, v148
	v_add_f32_e32 v140, v140, v156
	v_add_f32_e32 v140, v140, v164
	v_mul_f32_e32 v140, v204, v140
	v_fmac_f32_e32 v140, s89, v104
	v_mov_b32_e32 v104, v140
	v_sub_f32_e32 v105, v105, v238
	v_mul_f32_e32 v105, v105, v239
	v_fma_f32 v105, v105, v213, v221
	v_add_f32_e32 v141, v141, v149
	v_add_f32_e32 v141, v141, v157
	v_add_f32_e32 v141, v141, v165
	v_mul_f32_e32 v141, v205, v141
	v_fmac_f32_e32 v141, s89, v105
	v_mov_b32_e32 v105, v141
	v_sub_f32_e32 v106, v106, v238
	v_mul_f32_e32 v106, v106, v239
	v_fma_f32 v106, v106, v214, v222
	v_add_f32_e32 v142, v142, v150
	v_add_f32_e32 v142, v142, v158
	v_add_f32_e32 v142, v142, v166
	v_mul_f32_e32 v142, v206, v142
	v_fmac_f32_e32 v142, s89, v106
	v_mov_b32_e32 v106, v142
	v_sub_f32_e32 v107, v107, v238
	v_mul_f32_e32 v107, v107, v239
	v_fma_f32 v107, v107, v215, v223
	v_add_f32_e32 v143, v143, v151
	v_add_f32_e32 v143, v143, v159
	v_add_f32_e32 v143, v143, v167
	v_mul_f32_e32 v143, v207, v143
	v_fmac_f32_e32 v143, s89, v107
	v_mov_b32_e32 v107, v143
	global_store_dwordx4 v77, v[104:107], s[2:3] offset:0
	v_sub_f32_e32 v108, v108, v238
	v_mul_f32_e32 v108, v108, v239
	v_fma_f32 v108, v108, v216, v224
	v_add_f32_e32 v144, v144, v152
	v_add_f32_e32 v144, v144, v160
	v_add_f32_e32 v144, v144, v168
	v_mul_f32_e32 v144, v208, v144
	v_fmac_f32_e32 v144, s89, v108
	v_mov_b32_e32 v108, v144
	v_sub_f32_e32 v109, v109, v238
	v_mul_f32_e32 v109, v109, v239
	v_fma_f32 v109, v109, v217, v225
	v_add_f32_e32 v145, v145, v153
	v_add_f32_e32 v145, v145, v161
	v_add_f32_e32 v145, v145, v169
	v_mul_f32_e32 v145, v209, v145
	v_fmac_f32_e32 v145, s89, v109
	v_mov_b32_e32 v109, v145
	v_sub_f32_e32 v110, v110, v238
	v_mul_f32_e32 v110, v110, v239
	v_fma_f32 v110, v110, v218, v226
	v_add_f32_e32 v146, v146, v154
	v_add_f32_e32 v146, v146, v162
	v_add_f32_e32 v146, v146, v170
	v_mul_f32_e32 v146, v210, v146
	v_fmac_f32_e32 v146, s89, v110
	v_mov_b32_e32 v110, v146
	v_sub_f32_e32 v111, v111, v238
	v_mul_f32_e32 v111, v111, v239
	v_fma_f32 v111, v111, v219, v227
	v_add_f32_e32 v147, v147, v155
	v_add_f32_e32 v147, v147, v163
	v_add_f32_e32 v147, v147, v171
	v_mul_f32_e32 v147, v211, v147
	v_fmac_f32_e32 v147, s89, v111
	v_mov_b32_e32 v111, v147
	global_store_dwordx4 v77, v[108:111], s[2:3] offset:1024
	global_load_dwordx4 v[140:143], v77, s[4:5] offset:2048
	global_load_dwordx4 v[144:147], v77, s[4:5] offset:3072
	s_add_u32 s4, s4, 0x800000
	s_addc_u32 s5, s5, 0
	global_load_dwordx4 v[148:151], v77, s[4:5] offset:2048
	global_load_dwordx4 v[152:155], v77, s[4:5] offset:3072
	s_add_u32 s4, s4, 0x800000
	s_addc_u32 s5, s5, 0
	global_load_dwordx4 v[156:159], v77, s[4:5] offset:2048
	global_load_dwordx4 v[160:163], v77, s[4:5] offset:3072
	s_add_u32 s4, s4, 0x800000
	s_addc_u32 s5, s5, 0
	global_load_dwordx4 v[164:167], v77, s[4:5] offset:2048
	global_load_dwordx4 v[168:171], v77, s[4:5] offset:3072
	s_sub_u32 s4, s4, 0x1800000
	s_subb_u32 s5, s5, 0
	s_add_u32 s22, s50, 0x42000
	s_addc_u32 s23, s51, 0
	global_load_dwordx4 v[204:207], v77, s[22:23] offset:2048
	global_load_dwordx4 v[208:211], v77, s[22:23] offset:3072
	global_load_dwordx4 v[212:215], v77, s[64:65] offset:2048
	global_load_dwordx4 v[216:219], v77, s[64:65] offset:3072
	global_load_dwordx4 v[220:223], v77, s[66:67] offset:2048
	global_load_dwordx4 v[224:227], v77, s[66:67] offset:3072
	s_waitcnt vmcnt(0)
	v_sub_f32_e32 v112, v112, v238
	v_mul_f32_e32 v112, v112, v239
	v_fma_f32 v112, v112, v212, v220
	v_add_f32_e32 v140, v140, v148
	v_add_f32_e32 v140, v140, v156
	v_add_f32_e32 v140, v140, v164
	v_mul_f32_e32 v140, v204, v140
	v_fmac_f32_e32 v140, s89, v112
	v_mov_b32_e32 v112, v140
	v_sub_f32_e32 v113, v113, v238
	v_mul_f32_e32 v113, v113, v239
	v_fma_f32 v113, v113, v213, v221
	v_add_f32_e32 v141, v141, v149
	v_add_f32_e32 v141, v141, v157
	v_add_f32_e32 v141, v141, v165
	v_mul_f32_e32 v141, v205, v141
	v_fmac_f32_e32 v141, s89, v113
	v_mov_b32_e32 v113, v141
	v_sub_f32_e32 v114, v114, v238
	v_mul_f32_e32 v114, v114, v239
	v_fma_f32 v114, v114, v214, v222
	v_add_f32_e32 v142, v142, v150
	v_add_f32_e32 v142, v142, v158
	v_add_f32_e32 v142, v142, v166
	v_mul_f32_e32 v142, v206, v142
	v_fmac_f32_e32 v142, s89, v114
	v_mov_b32_e32 v114, v142
	v_sub_f32_e32 v115, v115, v238
	v_mul_f32_e32 v115, v115, v239
	v_fma_f32 v115, v115, v215, v223
	v_add_f32_e32 v143, v143, v151
	v_add_f32_e32 v143, v143, v159
	v_add_f32_e32 v143, v143, v167
	v_mul_f32_e32 v143, v207, v143
	v_fmac_f32_e32 v143, s89, v115
	v_mov_b32_e32 v115, v143
	global_store_dwordx4 v77, v[112:115], s[2:3] offset:2048
	v_sub_f32_e32 v116, v116, v238
	v_mul_f32_e32 v116, v116, v239
	v_fma_f32 v116, v116, v216, v224
	v_add_f32_e32 v144, v144, v152
	v_add_f32_e32 v144, v144, v160
	v_add_f32_e32 v144, v144, v168
	v_mul_f32_e32 v144, v208, v144
	v_fmac_f32_e32 v144, s89, v116
	v_mov_b32_e32 v116, v144
	v_sub_f32_e32 v117, v117, v238
	v_mul_f32_e32 v117, v117, v239
	v_fma_f32 v117, v117, v217, v225
	v_add_f32_e32 v145, v145, v153
	v_add_f32_e32 v145, v145, v161
	v_add_f32_e32 v145, v145, v169
	v_mul_f32_e32 v145, v209, v145
	v_fmac_f32_e32 v145, s89, v117
	v_mov_b32_e32 v117, v145
	v_sub_f32_e32 v118, v118, v238
	v_mul_f32_e32 v118, v118, v239
	v_fma_f32 v118, v118, v218, v226
	v_add_f32_e32 v146, v146, v154
	v_add_f32_e32 v146, v146, v162
	v_add_f32_e32 v146, v146, v170
	v_mul_f32_e32 v146, v210, v146
	v_fmac_f32_e32 v146, s89, v118
	v_mov_b32_e32 v118, v146
	v_sub_f32_e32 v119, v119, v238
	v_mul_f32_e32 v119, v119, v239
	v_fma_f32 v119, v119, v219, v227
	v_add_f32_e32 v147, v147, v155
	v_add_f32_e32 v147, v147, v163
	v_add_f32_e32 v147, v147, v171
	v_mul_f32_e32 v147, v211, v147
	v_fmac_f32_e32 v147, s89, v119
	v_mov_b32_e32 v119, v147
	global_store_dwordx4 v77, v[116:119], s[2:3] offset:3072
	s_branch .Ll0b_cpart_done
.Ll0b_done:
	s_waitcnt vmcnt(0)
	s_barrier
	s_and_saveexec_b64 s[0:1], s[24:25]
	s_cbranch_execz .LBB0_1971
	s_add_i32 s2, 0, 0x22000
	v_mov_b32_e32 v0, s2
	s_waitcnt vmcnt(0) expcnt(0) lgkmcnt(0)
	ds_read_b32 v2, v0
	s_add_i32 s2, 0, 0x22004
	v_mov_b32_e32 v0, s2
	ds_read_b32 v0, v0
	s_waitcnt lgkmcnt(1)
	v_cmp_ne_u32_e32 vcc, 0, v2
	s_cbranch_vccnz .LBB0_1935
	s_add_u32 s8, s50, 0x1000
	s_addc_u32 s9, s51, 0
	s_add_u32 s10, s50, 0x1100
	s_addc_u32 s11, s51, 0
	s_add_u32 s12, s50, 0x1200
	s_addc_u32 s13, s51, 0
	s_add_u32 s14, s50, 0x1300
	s_addc_u32 s15, s51, 0
	s_mov_b32 s2, 1
	v_mov_b32_e32 v16, 0
	s_branch .LBB0_1923

; DI void phase_ln(const Params& p, const float* gam, const float* bet, const float* modnext  , bool skip_ctx, bool final_out,
;                  const float* cgate  , const float* pg, const float* pb  ) {
;     ...
;     for (int rowA = gw; rowA < MR; rowA += 2 * nw) {
;         f32x4 v[2][8]; float sum[2] = {0.f, 0.f}; bool act[2]; int rows[2];
; #pragma unroll
;         for (int q = 0; q < 2; ++q) {
;             const int row = rowA + q * nw; rows[q] = row;
;             const int b = row / RB, r = row % RB;
;             act[q] = row < MR && !(skip_ctx && r < CL);
;             if (act[q]) {
;                 const bool cpart = cgate && r < CL;
;                 float pmu = 0.f, prs = 1.f;
;                 if (cpart && pg) { const float2 st = RS[row]; pmu = st.x; prs = st.y; }
; #pragma unroll
;                 for (int i = 0; i < 8; ++i) {
;                     const int col = (i * 64 + lane) * 4;
;                     v[q][i] = *(const f32x4*)(X + (size_t)row * DM + col);
;                     if (cpart) {
;                         if (pg) v[q][i] = (v[q][i] - pmu) * prs * *(const f32x4*)(pg + col) + *(const f32x4*)(pb + col);
;                         const float* pt = (const float*)(p.ws + WS_PART) + ((size_t)b * 256 + r) * DM + col;
;                         const f32x4 ps = *(const f32x4*)pt + *(const f32x4*)(pt + (size_t)1024 * DM) + *(const f32x4*)(pt + (size_t)2048 * DM) + *(const f32x4*)(pt + (size_t)3072 * DM);
;                         v[q][i] = v[q][i] * ALPHA + *(const f32x4*)(cgate + col) * ps;
;                         *(f32x4*)(X + (size_t)row * DM + col) = v[q][i];
;                     }
;                 }
;             } else {
; #pragma unroll
;                 for (int i = 0; i < 8; ++i) v[q][i] = (f32x4){0.f, 0.f, 0.f, 0.f};
;             }
;         }
; #pragma unroll
;         for (int q = 0; q < 2; ++q)
; #pragma unroll
;             for (int i = 0; i < 8; ++i) sum[q] += v[q][i][0] + v[q][i][1] + v[q][i][2] + v[q][i][3];
;         float mu[2], sq[2] = {0.f, 0.f}, rs[2];
; #pragma unroll
;         for (int o = 32; o > 0; o >>= 1) { sum[0] += __shfl_xor(sum[0], o); sum[1] += __shfl_xor(sum[1], o); }
; #pragma unroll
;         for (int q = 0; q < 2; ++q) {
;             mu[q] = sum[q] * (1.f / 2048.f);
; #pragma unroll
.LBB0_2895:
	s_or_b64 exec, exec, s[0:1]
	s_waitcnt lgkmcnt(0)
	v_mov_b32_e32 v0, v202
	s_barrier
	v_and_b32_e32 v80, 63, v202
	v_lshrrev_b32_e32 v81, 6, v202
	v_lshlrev_b32_e32 v76, 4, v80
	v_lshlrev_b32_e32 v78, 3, v80
	v_readfirstlane_b32 s35, v81
	v_add_u32_e32 v77, 0x1000, v76
	v_mov_b32_e32 v79, 0
	s_lshl_b32 s9, s26, 3
	s_lshl_b32 s11, s33, 3
	s_nop 0
	s_add_u32 s9, s9, s35
	s_mov_b32 s82, 0x3a000000
	s_mov_b32 s83, 0x3727c5ac
	s_mov_b32 s89, 0x3fb504f3
	s_add_u32 s22, s64, 0x2000
	s_addc_u32 s23, s65, 0
	global_load_dwordx4 v[12:15], v76, s[22:23] offset:0
	global_load_dwordx4 v[16:19], v76, s[22:23] offset:1024
	global_load_dwordx4 v[20:23], v76, s[22:23] offset:2048
	global_load_dwordx4 v[24:27], v76, s[22:23] offset:3072
	global_load_dwordx4 v[28:31], v77, s[22:23] offset:0
	global_load_dwordx4 v[32:35], v77, s[22:23] offset:1024
	global_load_dwordx4 v[36:39], v77, s[22:23] offset:2048
	global_load_dwordx4 v[40:43], v77, s[22:23] offset:3072
	s_add_u32 s22, s66, 0x2000
	s_addc_u32 s23, s67, 0
	global_load_dwordx4 v[44:47], v76, s[22:23] offset:0
	global_load_dwordx4 v[48:51], v76, s[22:23] offset:1024
	global_load_dwordx4 v[52:55], v76, s[22:23] offset:2048
	global_load_dwordx4 v[56:59], v76, s[22:23] offset:3072
	global_load_dwordx4 v[60:63], v77, s[22:23] offset:0
	global_load_dwordx4 v[64:67], v77, s[22:23] offset:1024
	global_load_dwordx4 v[68:71], v77, s[22:23] offset:2048
	global_load_dwordx4 v[72:75], v77, s[22:23] offset:3072
.Ll1a_row:
	s_cmpk_ge_u32 s9, 0x2400
	s_cbranch_scc1 .Ll1a_done
	s_lshr_b32 s35, s9, 8
	s_mul_i32 s27, s35, 57
	s_lshr_b32 s27, s27, 9
	s_mul_i32 s35, s27, 0x900
	s_sub_u32 s29, s9, s35
	s_cmpk_lt_u32 s29, 0x100
	s_cbranch_scc1 .Ll1a_next
	s_mov_b32 s32, s27
	s_lshl_b32 s35, s9, 13
	s_add_u32 s2, s50, 0xcba0000
	s_addc_u32 s3, s51, 0
	s_add_u32 s2, s2, s35
	s_addc_u32 s3, s3, 0
	global_load_dwordx4 v[88:91], v76, s[2:3] offset:0
	global_load_dwordx4 v[92:95], v76, s[2:3] offset:1024
	global_load_dwordx4 v[96:99], v76, s[2:3] offset:2048
	global_load_dwordx4 v[100:103], v76, s[2:3] offset:3072
	global_load_dwordx4 v[104:107], v77, s[2:3] offset:0
	global_load_dwordx4 v[108:111], v77, s[2:3] offset:1024
	global_load_dwordx4 v[112:115], v77, s[2:3] offset:2048
	global_load_dwordx4 v[116:119], v77, s[2:3] offset:3072
	s_mul_i32 s35, s32, 0xc000
	s_add_u32 s4, s50, 0x4a000
	s_addc_u32 s5, s51, 0
	s_add_u32 s4, s4, s35
	s_addc_u32 s5, s5, 0
	global_load_dwordx4 v[140:143], v76, s[4:5] offset:0
	global_load_dwordx4 v[144:147], v76, s[4:5] offset:1024
	global_load_dwordx4 v[148:151], v76, s[4:5] offset:2048
	global_load_dwordx4 v[152:155], v76, s[4:5] offset:3072
	global_load_dwordx4 v[156:159], v77, s[4:5] offset:0
	global_load_dwordx4 v[160:163], v77, s[4:5] offset:1024
	global_load_dwordx4 v[164:167], v77, s[4:5] offset:2048
	global_load_dwordx4 v[168:171], v77, s[4:5] offset:3072
	s_add_u32 s4, s4, 0x2000
	s_addc_u32 s5, s5, 0
	global_load_dwordx4 v[204:207], v76, s[4:5] offset:0
	global_load_dwordx4 v[208:211], v76, s[4:5] offset:1024
	global_load_dwordx4 v[212:215], v76, s[4:5] offset:2048
	global_load_dwordx4 v[216:219], v76, s[4:5] offset:3072
	global_load_dwordx4 v[220:223], v77, s[4:5] offset:0
	global_load_dwordx4 v[224:227], v77, s[4:5] offset:1024
	global_load_dwordx4 v[228:231], v77, s[4:5] offset:2048
	global_load_dwordx4 v[232:235], v77, s[4:5] offset:3072
	s_waitcnt vmcnt(16)
	v_add_f32_e32 v80, v88, v92
	v_add_f32_e32 v81, v89, v93
	v_add_f32_e32 v82, v90, v94
	v_add_f32_e32 v83, v91, v95
	v_add_f32_e32 v80, v96, v80
	v_add_f32_e32 v81, v97, v81
	v_add_f32_e32 v82, v98, v82
	v_add_f32_e32 v83, v99, v83
	v_add_f32_e32 v80, v100, v80
	v_add_f32_e32 v81, v101, v81
	v_add_f32_e32 v82, v102, v82
	v_add_f32_e32 v83, v103, v83
	v_add_f32_e32 v80, v104, v80
	v_add_f32_e32 v81, v105, v81
	v_add_f32_e32 v82, v106, v82
	v_add_f32_e32 v83, v107, v83
	v_add_f32_e32 v80, v108, v80
	v_add_f32_e32 v81, v109, v81
	v_add_f32_e32 v82, v110, v82
	v_add_f32_e32 v83, v111, v83
	v_add_f32_e32 v80, v112, v80
	v_add_f32_e32 v81, v113, v81
	v_add_f32_e32 v82, v114, v82
	v_add_f32_e32 v83, v115, v83
	v_add_f32_e32 v80, v116, v80
	v_add_f32_e32 v81, v117, v81
	v_add_f32_e32 v82, v118, v82
	v_add_f32_e32 v83, v119, v83
	v_add_f32_e32 v80, v80, v81
	v_add_f32_e32 v82, v82, v83
	v_add_f32_e32 v80, v80, v82
	s_nop 1
	v_add_f32_dpp v86, v80, v80 quad_perm:[1,0,3,2] row_mask:0xf bank_mask:0xf
	s_nop 1
	v_add_f32_dpp v86, v86, v86 quad_perm:[2,3,0,1] row_mask:0xf bank_mask:0xf
	s_nop 1
	v_add_f32_dpp v86, v86, v86 row_half_mirror row_mask:0xf bank_mask:0xf
	s_nop 1
	v_add_f32_dpp v86, v86, v86 row_mirror row_mask:0xf bank_mask:0xf
	s_nop 1
	v_readlane_b32 s69, v86, 0
	v_readlane_b32 s71, v86, 16
	v_readlane_b32 s73, v86, 32
	v_readlane_b32 s81, v86, 48
	s_nop 3
	v_mov_b32_e32 v84, s69
	v_add_f32_e32 v84, s71, v84
	v_add_f32_e32 v84, s73, v84
	v_add_f32_e32 v84, s81, v84
	v_mul_f32_e32 v236, s82, v84
	v_sub_f32_e32 v88, v88, v236
	v_sub_f32_e32 v89, v89, v236
	v_sub_f32_e32 v90, v90, v236
	v_sub_f32_e32 v91, v91, v236
	v_sub_f32_e32 v92, v92, v236
	v_sub_f32_e32 v93, v93, v236
	v_sub_f32_e32 v94, v94, v236
	v_sub_f32_e32 v95, v95, v236
	v_sub_f32_e32 v96, v96, v236
	v_sub_f32_e32 v97, v97, v236
	v_sub_f32_e32 v98, v98, v236
	v_sub_f32_e32 v99, v99, v236
	v_sub_f32_e32 v100, v100, v236
	v_sub_f32_e32 v101, v101, v236
	v_sub_f32_e32 v102, v102, v236
	v_sub_f32_e32 v103, v103, v236
	v_sub_f32_e32 v104, v104, v236
	v_sub_f32_e32 v105, v105, v236
	v_sub_f32_e32 v106, v106, v236
	v_sub_f32_e32 v107, v107, v236
	v_sub_f32_e32 v108, v108, v236
	v_sub_f32_e32 v109, v109, v236
	v_sub_f32_e32 v110, v110, v236
	v_sub_f32_e32 v111, v111, v236
; DI void phase_ln(const Params& p, const float* gam, const float* bet, const float* modnext  , bool skip_ctx, bool final_out,
;                  const float* cgate  , const float* pg, const float* pb  ) {
;     ...
;             for (int i = 0; i < 8; ++i) { v[q][i] -= mu[q]; sq[q] += v[q][i][0] * v[q][i][0] + v[q][i][1] * v[q][i][1] + v[q][i][2] * v[q][i][2] + v[q][i][3] * v[q][i][3]; }
;         }
; #pragma unroll
;         for (int o = 32; o > 0; o >>= 1) { sq[0] += __shfl_xor(sq[0], o); sq[1] += __shfl_xor(sq[1], o); }
; #pragma unroll
;         for (int q = 0; q < 2; ++q) {
;             if (!act[q]) continue;
;             rs[q] = rsqrtf(sq[q] * (1.f / 2048.f) + 1e-5f);
;             const int row = rows[q]; const int b = row / RB, r = row % RB; const int s = r < CL ? 4 : b;
;             if (lane == 0 && !final_out) RS[row] = make_float2(mu[q], rs[q]);
	v_sub_f32_e32 v112, v112, v236
	v_sub_f32_e32 v113, v113, v236
	v_sub_f32_e32 v114, v114, v236
	v_sub_f32_e32 v115, v115, v236
	v_sub_f32_e32 v116, v116, v236
	v_sub_f32_e32 v117, v117, v236
	v_sub_f32_e32 v118, v118, v236
	v_sub_f32_e32 v119, v119, v236
	v_mul_f32_e32 v80, v88, v88
	v_mul_f32_e32 v81, v89, v89
	v_mul_f32_e32 v82, v90, v90
	v_mul_f32_e32 v83, v91, v91
	v_fmac_f32_e32 v80, v92, v92
	v_fmac_f32_e32 v81, v93, v93
	v_fmac_f32_e32 v82, v94, v94
	v_fmac_f32_e32 v83, v95, v95
	v_fmac_f32_e32 v80, v96, v96
	v_fmac_f32_e32 v81, v97, v97
	v_fmac_f32_e32 v82, v98, v98
	v_fmac_f32_e32 v83, v99, v99
	v_fmac_f32_e32 v80, v100, v100
	v_fmac_f32_e32 v81, v101, v101
	v_fmac_f32_e32 v82, v102, v102
	v_fmac_f32_e32 v83, v103, v103
	v_fmac_f32_e32 v80, v104, v104
	v_fmac_f32_e32 v81, v105, v105
	v_fmac_f32_e32 v82, v106, v106
	v_fmac_f32_e32 v83, v107, v107
	v_fmac_f32_e32 v80, v108, v108
	v_fmac_f32_e32 v81, v109, v109
	v_fmac_f32_e32 v82, v110, v110
	v_fmac_f32_e32 v83, v111, v111
	v_fmac_f32_e32 v80, v112, v112
	v_fmac_f32_e32 v81, v113, v113
	v_fmac_f32_e32 v82, v114, v114
	v_fmac_f32_e32 v83, v115, v115
	v_fmac_f32_e32 v80, v116, v116
	v_fmac_f32_e32 v81, v117, v117
	v_fmac_f32_e32 v82, v118, v118
	v_fmac_f32_e32 v83, v119, v119
	v_add_f32_e32 v80, v80, v81
	v_add_f32_e32 v82, v82, v83
	v_add_f32_e32 v80, v80, v82
	s_nop 1
	v_add_f32_dpp v86, v80, v80 quad_perm:[1,0,3,2] row_mask:0xf bank_mask:0xf
	s_nop 1
	v_add_f32_dpp v86, v86, v86 quad_perm:[2,3,0,1] row_mask:0xf bank_mask:0xf
	s_nop 1
	v_add_f32_dpp v86, v86, v86 row_half_mirror row_mask:0xf bank_mask:0xf
	s_nop 1
	v_add_f32_dpp v86, v86, v86 row_mirror row_mask:0xf bank_mask:0xf
	s_nop 1
	v_readlane_b32 s69, v86, 0
	v_readlane_b32 s71, v86, 16
	v_readlane_b32 s73, v86, 32
	v_readlane_b32 s81, v86, 48
	s_nop 3
	v_mov_b32_e32 v84, s69
	v_add_f32_e32 v84, s71, v84
	v_add_f32_e32 v84, s73, v84
	v_add_f32_e32 v84, s81, v84
	v_mov_b32_e32 v86, s83
	v_fmac_f32_e32 v86, s82, v84
	v_rsq_f32_e32 v237, v86
	s_nop 0
	s_lshl_b32 s35, s9, 3
	s_add_u32 s22, s50, 0x260a0000
	s_addc_u32 s23, s51, 0
	s_add_u32 s22, s22, s35
	s_addc_u32 s23, s23, 0
	s_mov_b64 s[74:75], exec
	s_mov_b64 exec, 1
	global_store_dwordx2 v79, v[236:237], s[22:23]
	s_mov_b64 exec, s[74:75]
	s_lshl_b32 s35, s9, 12
	s_add_u32 s6, s50, 0x23ca0000
	s_addc_u32 s7, s51, 0
	s_add_u32 s6, s6, s35
	s_addc_u32 s7, s7, 0
	s_waitcnt vmcnt(1)
; DI void st_bf16x4(bf16_t* p, f32x4 v) { u32x2 w; w.x = cvt_pk_bf16(v[0], v[1]); w.y = cvt_pk_bf16(v[2], v[3]); *(u32x2*)p = w; }
; DI void phase_ln(const Params& p, const float* gam, const float* bet, const float* modnext  , bool skip_ctx, bool final_out,
;                  const float* cgate  , const float* pg, const float* pb  ) {
;     ...
; #pragma unroll
;             for (int i = 0; i < 8; ++i) {
;                 const int col = (i * 64 + lane) * 4;
;                 const f32x4 o = v[q][i] * rs[q] * *(const f32x4*)(gam + col) + *(const f32x4*)(bet + col);
;                 if (final_out) { *(f32x4*)(p.out + ((size_t)b * TL + (r - CL)) * DM + col) = o; }
;                 else {
;                     const f32x4 s4 = *(const f32x4*)(modnext + (size_t)s * 12288 + col), c4 = *(const f32x4*)(modnext + (size_t)s * 12288 + 2048 + col);
;                     st_bf16x4(H + (size_t)row * DM + col, o * (c4 + 1.f) + s4);
;                 }
	v_mul_f32_e32 v88, v88, v237
	v_mul_f32_e32 v89, v89, v237
	v_mul_f32_e32 v90, v90, v237
	v_mul_f32_e32 v91, v91, v237
	v_fma_f32 v88, v88, v12, v44
	v_fma_f32 v89, v89, v13, v45
	v_fma_f32 v90, v90, v14, v46
	v_fma_f32 v91, v91, v15, v47
	v_add_f32_e32 v204, 1.0, v204
	v_add_f32_e32 v205, 1.0, v205
	v_add_f32_e32 v206, 1.0, v206
	v_add_f32_e32 v207, 1.0, v207
	v_fma_f32 v88, v88, v204, v140
	v_fma_f32 v89, v89, v205, v141
	v_fma_f32 v90, v90, v206, v142
	v_fma_f32 v91, v91, v207, v143
	v_cvt_pk_bf16_f32 v88, v88, v89
	v_cvt_pk_bf16_f32 v89, v90, v91
	global_store_dwordx2 v78, v[88:89], s[6:7] offset:0
	v_mul_f32_e32 v92, v92, v237
	v_mul_f32_e32 v93, v93, v237
	v_mul_f32_e32 v94, v94, v237
	v_mul_f32_e32 v95, v95, v237
	v_fma_f32 v92, v92, v16, v48
	v_fma_f32 v93, v93, v17, v49
	v_fma_f32 v94, v94, v18, v50
	v_fma_f32 v95, v95, v19, v51
	v_add_f32_e32 v208, 1.0, v208
	v_add_f32_e32 v209, 1.0, v209
	v_add_f32_e32 v210, 1.0, v210
	v_add_f32_e32 v211, 1.0, v211
	v_fma_f32 v92, v92, v208, v144
	v_fma_f32 v93, v93, v209, v145
	v_fma_f32 v94, v94, v210, v146
	v_fma_f32 v95, v95, v211, v147
	v_cvt_pk_bf16_f32 v92, v92, v93
	v_cvt_pk_bf16_f32 v93, v94, v95
	global_store_dwordx2 v78, v[92:93], s[6:7] offset:512
	v_mul_f32_e32 v96, v96, v237
	v_mul_f32_e32 v97, v97, v237
	v_mul_f32_e32 v98, v98, v237
	v_mul_f32_e32 v99, v99, v237
	v_fma_f32 v96, v96, v20, v52
	v_fma_f32 v97, v97, v21, v53
	v_fma_f32 v98, v98, v22, v54
	v_fma_f32 v99, v99, v23, v55
	v_add_f32_e32 v212, 1.0, v212
	v_add_f32_e32 v213, 1.0, v213
	v_add_f32_e32 v214, 1.0, v214
	v_add_f32_e32 v215, 1.0, v215
	v_fma_f32 v96, v96, v212, v148
	v_fma_f32 v97, v97, v213, v149
	v_fma_f32 v98, v98, v214, v150
	v_fma_f32 v99, v99, v215, v151
	v_cvt_pk_bf16_f32 v96, v96, v97
	v_cvt_pk_bf16_f32 v97, v98, v99
	global_store_dwordx2 v78, v[96:97], s[6:7] offset:1024
	v_mul_f32_e32 v100, v100, v237
	v_mul_f32_e32 v101, v101, v237
	v_mul_f32_e32 v102, v102, v237
	v_mul_f32_e32 v103, v103, v237
	v_fma_f32 v100, v100, v24, v56
	v_fma_f32 v101, v101, v25, v57
	v_fma_f32 v102, v102, v26, v58
	v_fma_f32 v103, v103, v27, v59
	v_add_f32_e32 v216, 1.0, v216
	v_add_f32_e32 v217, 1.0, v217
	v_add_f32_e32 v218, 1.0, v218
	v_add_f32_e32 v219, 1.0, v219
	v_fma_f32 v100, v100, v216, v152
	v_fma_f32 v101, v101, v217, v153
	v_fma_f32 v102, v102, v218, v154
	v_fma_f32 v103, v103, v219, v155
	v_cvt_pk_bf16_f32 v100, v100, v101
	v_cvt_pk_bf16_f32 v101, v102, v103
	global_store_dwordx2 v78, v[100:101], s[6:7] offset:1536
	v_mul_f32_e32 v104, v104, v237
	v_mul_f32_e32 v105, v105, v237
	v_mul_f32_e32 v106, v106, v237
	v_mul_f32_e32 v107, v107, v237
	v_fma_f32 v104, v104, v28, v60
	v_fma_f32 v105, v105, v29, v61
	v_fma_f32 v106, v106, v30, v62
	v_fma_f32 v107, v107, v31, v63
	v_add_f32_e32 v220, 1.0, v220
	v_add_f32_e32 v221, 1.0, v221
	v_add_f32_e32 v222, 1.0, v222
	v_add_f32_e32 v223, 1.0, v223
	v_fma_f32 v104, v104, v220, v156
	v_fma_f32 v105, v105, v221, v157
	v_fma_f32 v106, v106, v222, v158
	v_fma_f32 v107, v107, v223, v159
	v_cvt_pk_bf16_f32 v104, v104, v105
	v_cvt_pk_bf16_f32 v105, v106, v107
	global_store_dwordx2 v78, v[104:105], s[6:7] offset:2048
	v_mul_f32_e32 v108, v108, v237
	v_mul_f32_e32 v109, v109, v237
	v_mul_f32_e32 v110, v110, v237
	v_mul_f32_e32 v111, v111, v237
	v_fma_f32 v108, v108, v32, v64
	v_fma_f32 v109, v109, v33, v65
	v_fma_f32 v110, v110, v34, v66
	v_fma_f32 v111, v111, v35, v67
	v_add_f32_e32 v224, 1.0, v224
	v_add_f32_e32 v225, 1.0, v225
	v_add_f32_e32 v226, 1.0, v226
	v_add_f32_e32 v227, 1.0, v227
	v_fma_f32 v108, v108, v224, v160
	v_fma_f32 v109, v109, v225, v161
	v_fma_f32 v110, v110, v226, v162
	v_fma_f32 v111, v111, v227, v163
	v_cvt_pk_bf16_f32 v108, v108, v109
	v_cvt_pk_bf16_f32 v109, v110, v111
	global_store_dwordx2 v78, v[108:109], s[6:7] offset:2560
	v_mul_f32_e32 v112, v112, v237
	v_mul_f32_e32 v113, v113, v237
	v_mul_f32_e32 v114, v114, v237
	v_mul_f32_e32 v115, v115, v237
	v_fma_f32 v112, v112, v36, v68
	v_fma_f32 v113, v113, v37, v69
	v_fma_f32 v114, v114, v38, v70
	v_fma_f32 v115, v115, v39, v71
	v_add_f32_e32 v228, 1.0, v228
	v_add_f32_e32 v229, 1.0, v229
	v_add_f32_e32 v230, 1.0, v230
	v_add_f32_e32 v231, 1.0, v231
	v_fma_f32 v112, v112, v228, v164
	v_fma_f32 v113, v113, v229, v165
	v_fma_f32 v114, v114, v230, v166
	v_fma_f32 v115, v115, v231, v167
	v_cvt_pk_bf16_f32 v112, v112, v113
	v_cvt_pk_bf16_f32 v113, v114, v115
	global_store_dwordx2 v78, v[112:113], s[6:7] offset:3072
	v_mul_f32_e32 v116, v116, v237
	v_mul_f32_e32 v117, v117, v237
	v_mul_f32_e32 v118, v118, v237
	v_mul_f32_e32 v119, v119, v237
	v_fma_f32 v116, v116, v40, v72
	v_fma_f32 v117, v117, v41, v73
	v_fma_f32 v118, v118, v42, v74
	v_fma_f32 v119, v119, v43, v75
	v_add_f32_e32 v232, 1.0, v232
	v_add_f32_e32 v233, 1.0, v233
	v_add_f32_e32 v234, 1.0, v234
	v_add_f32_e32 v235, 1.0, v235
	v_fma_f32 v116, v116, v232, v168
	v_fma_f32 v117, v117, v233, v169
	v_fma_f32 v118, v118, v234, v170
	v_fma_f32 v119, v119, v235, v171
	v_cvt_pk_bf16_f32 v116, v116, v117
	v_cvt_pk_bf16_f32 v117, v118, v119
	global_store_dwordx2 v78, v[116:117], s[6:7] offset:3584

; DI int otid() { int t = threadIdx.x; asm volatile("" : "+v"(t)); return t; }
; DI void phase_ln(const Params& p, const float* gam, const float* bet, const float* modnext  , bool skip_ctx, bool final_out,
;                  const float* cgate  , const float* pg, const float* pb  ) {
;     const int tid_ = otid(); const int lane = tid_ & 63, gw = blockIdx.x * 8 + (tid_ >> 6), nw = gridDim.x * 8;
;     float* X = (float*)(p.ws + WS_X); bf16_t* H = (bf16_t*)(p.ws + WS_H); float2* RS = (float2*)(p.ws + WS_RSTAT);
;     for (int rowA = gw; rowA < MR; rowA += 2 * nw) {
;         f32x4 v[2][8]; float sum[2] = {0.f, 0.f}; bool act[2]; int rows[2];
; #pragma unroll
;         for (int q = 0; q < 2; ++q) {
;             const int row = rowA + q * nw; rows[q] = row;
;             const int b = row / RB, r = row % RB;
;             act[q] = row < MR && !(skip_ctx && r < CL);
;             if (act[q]) {
;                 const bool cpart = cgate && r < CL;
;                 float pmu = 0.f, prs = 1.f;
;                 if (cpart && pg) { const float2 st = RS[row]; pmu = st.x; prs = st.y; }
; #pragma unroll
;                 for (int i = 0; i < 8; ++i) {
;                     const int col = (i * 64 + lane) * 4;
;                     v[q][i] = *(const f32x4*)(X + (size_t)row * DM + col);
.LBB0_3170:
	s_or_b64 exec, exec, s[0:1]
	s_waitcnt lgkmcnt(0)
	s_barrier
	v_and_b32_e32 v80, 63, v202
	v_lshrrev_b32_e32 v81, 6, v202
	v_lshlrev_b32_e32 v76, 4, v80
	v_lshlrev_b32_e32 v78, 3, v80
	v_readfirstlane_b32 s35, v81
	v_add_u32_e32 v77, 0x1000, v76
	v_mov_b32_e32 v79, 0
	s_lshl_b32 s9, s26, 3
	s_lshl_b32 s11, s33, 3
	s_nop 0
	s_add_u32 s9, s9, s35
	s_mov_b32 s82, 0x3a000000
	s_mov_b32 s83, 0x3727c5ac
	s_mov_b32 s89, 0x3fb504f3
	s_add_u32 s22, s44, 0x2000
	s_addc_u32 s23, s45, 0
	global_load_dwordx4 v[12:15], v76, s[22:23] offset:0
	global_load_dwordx4 v[16:19], v76, s[22:23] offset:1024
	global_load_dwordx4 v[20:23], v76, s[22:23] offset:2048
	global_load_dwordx4 v[24:27], v76, s[22:23] offset:3072
	global_load_dwordx4 v[28:31], v77, s[22:23] offset:0
	global_load_dwordx4 v[32:35], v77, s[22:23] offset:1024
	global_load_dwordx4 v[36:39], v77, s[22:23] offset:2048
	global_load_dwordx4 v[40:43], v77, s[22:23] offset:3072
	s_add_u32 s22, s46, 0x2000
	s_addc_u32 s23, s47, 0
	global_load_dwordx4 v[44:47], v76, s[22:23] offset:0
	global_load_dwordx4 v[48:51], v76, s[22:23] offset:1024
	global_load_dwordx4 v[52:55], v76, s[22:23] offset:2048
	global_load_dwordx4 v[56:59], v76, s[22:23] offset:3072
	global_load_dwordx4 v[60:63], v77, s[22:23] offset:0
	global_load_dwordx4 v[64:67], v77, s[22:23] offset:1024
	global_load_dwordx4 v[68:71], v77, s[22:23] offset:2048
	global_load_dwordx4 v[72:75], v77, s[22:23] offset:3072
.Lfin_row:
	s_cmpk_ge_u32 s9, 0x2400
	s_cbranch_scc1 .Lfin_done
	s_lshr_b32 s35, s9, 8
	s_mul_i32 s27, s35, 57
	s_lshr_b32 s27, s27, 9
	s_mul_i32 s35, s27, 0x900
	s_sub_u32 s29, s9, s35
	s_cmpk_lt_u32 s29, 0x100
	s_cbranch_scc1 .Lfin_next
	s_mov_b32 s32, s27
	s_lshl_b32 s35, s9, 13
	s_add_u32 s2, s50, 0xcba0000
	s_addc_u32 s3, s51, 0
	s_add_u32 s2, s2, s35
	s_addc_u32 s3, s3, 0
	global_load_dwordx4 v[88:91], v76, s[2:3] offset:0
	global_load_dwordx4 v[92:95], v76, s[2:3] offset:1024
	global_load_dwordx4 v[96:99], v76, s[2:3] offset:2048
	global_load_dwordx4 v[100:103], v76, s[2:3] offset:3072
	global_load_dwordx4 v[104:107], v77, s[2:3] offset:0
	global_load_dwordx4 v[108:111], v77, s[2:3] offset:1024
	global_load_dwordx4 v[112:115], v77, s[2:3] offset:2048
	global_load_dwordx4 v[116:119], v77, s[2:3] offset:3072
	s_waitcnt vmcnt(0)
; DI void phase_ln(const Params& p, const float* gam, const float* bet, const float* modnext  , bool skip_ctx, bool final_out,
;                  const float* cgate  , const float* pg, const float* pb  ) {
;     ...
; #pragma unroll
;         for (int q = 0; q < 2; ++q)
; #pragma unroll
;             for (int i = 0; i < 8; ++i) sum[q] += v[q][i][0] + v[q][i][1] + v[q][i][2] + v[q][i][3];
;         float mu[2], sq[2] = {0.f, 0.f}, rs[2];
; #pragma unroll
;         for (int o = 32; o > 0; o >>= 1) { sum[0] += __shfl_xor(sum[0], o); sum[1] += __shfl_xor(sum[1], o); }
; #pragma unroll
;         for (int q = 0; q < 2; ++q) {
;             mu[q] = sum[q] * (1.f / 2048.f);
; #pragma unroll
;             for (int i = 0; i < 8; ++i) { v[q][i] -= mu[q]; sq[q] += v[q][i][0] * v[q][i][0] + v[q][i][1] * v[q][i][1] + v[q][i][2] * v[q][i][2] + v[q][i][3] * v[q][i][3]; }
;         }
; #pragma unroll
;         for (int o = 32; o > 0; o >>= 1) { sq[0] += __shfl_xor(sq[0], o); sq[1] += __shfl_xor(sq[1], o); }
; #pragma unroll
;         for (int q = 0; q < 2; ++q) {
;             if (!act[q]) continue;
;             rs[q] = rsqrtf(sq[q] * (1.f / 2048.f) + 1e-5f);
;             const int row = rows[q]; const int b = row / RB, r = row % RB; const int s = r < CL ? 4 : b;
;             if (lane == 0 && !final_out) RS[row] = make_float2(mu[q], rs[q]);
; #pragma unroll
;             for (int i = 0; i < 8; ++i) {
;                 const int col = (i * 64 + lane) * 4;
;                 const f32x4 o = v[q][i] * rs[q] * *(const f32x4*)(gam + col) + *(const f32x4*)(bet + col);
;                 if (final_out) { *(f32x4*)(p.out + ((size_t)b * TL + (r - CL)) * DM + col) = o; }
	v_add_f32_e32 v80, v88, v92
	v_add_f32_e32 v81, v89, v93
	v_add_f32_e32 v82, v90, v94
	v_add_f32_e32 v83, v91, v95
	v_add_f32_e32 v80, v96, v80
	v_add_f32_e32 v81, v97, v81
	v_add_f32_e32 v82, v98, v82
	v_add_f32_e32 v83, v99, v83
	v_add_f32_e32 v80, v100, v80
	v_add_f32_e32 v81, v101, v81
	v_add_f32_e32 v82, v102, v82
	v_add_f32_e32 v83, v103, v83
	v_add_f32_e32 v80, v104, v80
	v_add_f32_e32 v81, v105, v81
	v_add_f32_e32 v82, v106, v82
	v_add_f32_e32 v83, v107, v83
	v_add_f32_e32 v80, v108, v80
	v_add_f32_e32 v81, v109, v81
	v_add_f32_e32 v82, v110, v82
	v_add_f32_e32 v83, v111, v83
	v_add_f32_e32 v80, v112, v80
	v_add_f32_e32 v81, v113, v81
	v_add_f32_e32 v82, v114, v82
	v_add_f32_e32 v83, v115, v83
	v_add_f32_e32 v80, v116, v80
	v_add_f32_e32 v81, v117, v81
	v_add_f32_e32 v82, v118, v82
	v_add_f32_e32 v83, v119, v83
	v_add_f32_e32 v80, v80, v81
	v_add_f32_e32 v82, v82, v83
	v_add_f32_e32 v80, v80, v82
	s_nop 1
	v_add_f32_dpp v86, v80, v80 quad_perm:[1,0,3,2] row_mask:0xf bank_mask:0xf
	s_nop 1
	v_add_f32_dpp v86, v86, v86 quad_perm:[2,3,0,1] row_mask:0xf bank_mask:0xf
	s_nop 1
	v_add_f32_dpp v86, v86, v86 row_half_mirror row_mask:0xf bank_mask:0xf
	s_nop 1
	v_add_f32_dpp v86, v86, v86 row_mirror row_mask:0xf bank_mask:0xf
	s_nop 1
	v_readlane_b32 s69, v86, 0
	v_readlane_b32 s71, v86, 16
	v_readlane_b32 s73, v86, 32
	v_readlane_b32 s81, v86, 48
	s_nop 3
	v_mov_b32_e32 v84, s69
	v_add_f32_e32 v84, s71, v84
	v_add_f32_e32 v84, s73, v84
	v_add_f32_e32 v84, s81, v84
	v_mul_f32_e32 v236, s82, v84
	v_sub_f32_e32 v88, v88, v236
	v_sub_f32_e32 v89, v89, v236
	v_sub_f32_e32 v90, v90, v236
	v_sub_f32_e32 v91, v91, v236
	v_sub_f32_e32 v92, v92, v236
	v_sub_f32_e32 v93, v93, v236
	v_sub_f32_e32 v94, v94, v236
	v_sub_f32_e32 v95, v95, v236
	v_sub_f32_e32 v96, v96, v236
	v_sub_f32_e32 v97, v97, v236
	v_sub_f32_e32 v98, v98, v236
	v_sub_f32_e32 v99, v99, v236
	v_sub_f32_e32 v100, v100, v236
	v_sub_f32_e32 v101, v101, v236
	v_sub_f32_e32 v102, v102, v236
	v_sub_f32_e32 v103, v103, v236
	v_sub_f32_e32 v104, v104, v236
	v_sub_f32_e32 v105, v105, v236
	v_sub_f32_e32 v106, v106, v236
	v_sub_f32_e32 v107, v107, v236
	v_sub_f32_e32 v108, v108, v236
	v_sub_f32_e32 v109, v109, v236
	v_sub_f32_e32 v110, v110, v236
	v_sub_f32_e32 v111, v111, v236
	v_sub_f32_e32 v112, v112, v236
	v_sub_f32_e32 v113, v113, v236
	v_sub_f32_e32 v114, v114, v236
	v_sub_f32_e32 v115, v115, v236
	v_sub_f32_e32 v116, v116, v236
	v_sub_f32_e32 v117, v117, v236
	v_sub_f32_e32 v118, v118, v236
	v_sub_f32_e32 v119, v119, v236
	v_mul_f32_e32 v80, v88, v88
	v_mul_f32_e32 v81, v89, v89
	v_mul_f32_e32 v82, v90, v90
	v_mul_f32_e32 v83, v91, v91
	v_fmac_f32_e32 v80, v92, v92
	v_fmac_f32_e32 v81, v93, v93
	v_fmac_f32_e32 v82, v94, v94
	v_fmac_f32_e32 v83, v95, v95
	v_fmac_f32_e32 v80, v96, v96
	v_fmac_f32_e32 v81, v97, v97
	v_fmac_f32_e32 v82, v98, v98
	v_fmac_f32_e32 v83, v99, v99
	v_fmac_f32_e32 v80, v100, v100
	v_fmac_f32_e32 v81, v101, v101
	v_fmac_f32_e32 v82, v102, v102
	v_fmac_f32_e32 v83, v103, v103
	v_fmac_f32_e32 v80, v104, v104
	v_fmac_f32_e32 v81, v105, v105
	v_fmac_f32_e32 v82, v106, v106
	v_fmac_f32_e32 v83, v107, v107
	v_fmac_f32_e32 v80, v108, v108
	v_fmac_f32_e32 v81, v109, v109
	v_fmac_f32_e32 v82, v110, v110
	v_fmac_f32_e32 v83, v111, v111
	v_fmac_f32_e32 v80, v112, v112
	v_fmac_f32_e32 v81, v113, v113
	v_fmac_f32_e32 v82, v114, v114
	v_fmac_f32_e32 v83, v115, v115
	v_fmac_f32_e32 v80, v116, v116
	v_fmac_f32_e32 v81, v117, v117
	v_fmac_f32_e32 v82, v118, v118
	v_fmac_f32_e32 v83, v119, v119
	v_add_f32_e32 v80, v80, v81
	v_add_f32_e32 v82, v82, v83
	v_add_f32_e32 v80, v80, v82
	s_nop 1
	v_add_f32_dpp v86, v80, v80 quad_perm:[1,0,3,2] row_mask:0xf bank_mask:0xf
	s_nop 1
	v_add_f32_dpp v86, v86, v86 quad_perm:[2,3,0,1] row_mask:0xf bank_mask:0xf
	s_nop 1
	v_add_f32_dpp v86, v86, v86 row_half_mirror row_mask:0xf bank_mask:0xf
	s_nop 1
	v_add_f32_dpp v86, v86, v86 row_mirror row_mask:0xf bank_mask:0xf
	s_nop 1
	v_readlane_b32 s69, v86, 0
	v_readlane_b32 s71, v86, 16
	v_readlane_b32 s73, v86, 32
	v_readlane_b32 s81, v86, 48
	s_nop 3
	v_mov_b32_e32 v84, s69
	v_add_f32_e32 v84, s71, v84
	v_add_f32_e32 v84, s73, v84
	v_add_f32_e32 v84, s81, v84
	v_mov_b32_e32 v86, s83
	v_fmac_f32_e32 v86, s82, v84
	v_rsq_f32_e32 v237, v86
	s_nop 0
	s_lshl_b32 s35, s27, 11
	s_add_u32 s35, s35, s29
	s_sub_u32 s35, s35, 0x100
	s_lshl_b32 s35, s35, 13
	s_add_u32 s6, s48, s35
	s_addc_u32 s7, s49, 0
	v_mul_f32_e32 v88, v88, v237
	v_mul_f32_e32 v89, v89, v237
	v_mul_f32_e32 v90, v90, v237
	v_mul_f32_e32 v91, v91, v237
	v_fma_f32 v88, v88, v12, v44
	v_fma_f32 v89, v89, v13, v45
	v_fma_f32 v90, v90, v14, v46
	v_fma_f32 v91, v91, v15, v47
	global_store_dwordx4 v76, v[88:91], s[6:7] offset:0
	v_mul_f32_e32 v92, v92, v237
	v_mul_f32_e32 v93, v93, v237
	v_mul_f32_e32 v94, v94, v237
	v_mul_f32_e32 v95, v95, v237
	v_fma_f32 v92, v92, v16, v48
	v_fma_f32 v93, v93, v17, v49
	v_fma_f32 v94, v94, v18, v50
	v_fma_f32 v95, v95, v19, v51
	global_store_dwordx4 v76, v[92:95], s[6:7] offset:1024
	v_mul_f32_e32 v96, v96, v237
	v_mul_f32_e32 v97, v97, v237
	v_mul_f32_e32 v98, v98, v237
	v_mul_f32_e32 v99, v99, v237
	v_fma_f32 v96, v96, v20, v52
	v_fma_f32 v97, v97, v21, v53
	v_fma_f32 v98, v98, v22, v54
	v_fma_f32 v99, v99, v23, v55
	global_store_dwordx4 v76, v[96:99], s[6:7] offset:2048
	v_mul_f32_e32 v100, v100, v237
	v_mul_f32_e32 v101, v101, v237
	v_mul_f32_e32 v102, v102, v237
	v_mul_f32_e32 v103, v103, v237
	v_fma_f32 v100, v100, v24, v56
	v_fma_f32 v101, v101, v25, v57
	v_fma_f32 v102, v102, v26, v58
	v_fma_f32 v103, v103, v27, v59
	global_store_dwordx4 v76, v[100:103], s[6:7] offset:3072
	v_mul_f32_e32 v104, v104, v237
	v_mul_f32_e32 v105, v105, v237
	v_mul_f32_e32 v106, v106, v237
	v_mul_f32_e32 v107, v107, v237
	v_fma_f32 v104, v104, v28, v60
	v_fma_f32 v105, v105, v29, v61
	v_fma_f32 v106, v106, v30, v62
	v_fma_f32 v107, v107, v31, v63
	global_store_dwordx4 v77, v[104:107], s[6:7] offset:0
	v_mul_f32_e32 v108, v108, v237
	v_mul_f32_e32 v109, v109, v237
	v_mul_f32_e32 v110, v110, v237
	v_mul_f32_e32 v111, v111, v237
	v_fma_f32 v108, v108, v32, v64
	v_fma_f32 v109, v109, v33, v65
	v_fma_f32 v110, v110, v34, v66
	v_fma_f32 v111, v111, v35, v67
	global_store_dwordx4 v77, v[108:111], s[6:7] offset:1024
	v_mul_f32_e32 v112, v112, v237
	v_mul_f32_e32 v113, v113, v237
	v_mul_f32_e32 v114, v114, v237
	v_mul_f32_e32 v115, v115, v237
	v_fma_f32 v112, v112, v36, v68
	v_fma_f32 v113, v113, v37, v69
	v_fma_f32 v114, v114, v38, v70
	v_fma_f32 v115, v115, v39, v71
	global_store_dwordx4 v77, v[112:115], s[6:7] offset:2048
	v_mul_f32_e32 v116, v116, v237
	v_mul_f32_e32 v117, v117, v237
	v_mul_f32_e32 v118, v118, v237
	v_mul_f32_e32 v119, v119, v237
	v_fma_f32 v116, v116, v40, v72
	v_fma_f32 v117, v117, v41, v73
	v_fma_f32 v118, v118, v42, v74
	v_fma_f32 v119, v119, v43, v75
	global_store_dwordx4 v77, v[116:119], s[6:7] offset:3072
